# static s_setprio 1 for waves 4-7 in the GEMM K-loops, hipcc per-block setprio flips deleted
# speedup vs baseline: 1.0083x; 1.0007x over previous
.LBB0_450:
	s_ashr_i32 s21, s20, 31
	s_lshl_b64 s[24:25], s[20:21], 19
	s_add_u32 s24, s2, s24
	s_addc_u32 s25, s3, s25
	s_and_b64 s[26:27], s[10:11], exec
	s_cselect_b32 s21, s25, s31
	s_cselect_b32 s84, s24, s30
	s_ashr_i32 s13, s12, 31
	s_lshl_b64 s[26:27], s[12:13], 19
	s_add_u32 s26, s18, s26
	s_addc_u32 s27, s19, s27
	s_and_b64 s[34:35], s[10:11], exec
	s_cselect_b32 s13, s27, s29
	s_cselect_b32 s85, s26, s28
	s_add_u32 s86, s28, 0x100
	s_addc_u32 s87, s29, 0
	s_add_u32 s28, s30, 0x40080
	v_mov_b32_e32 v2, 0
	s_addc_u32 s29, s31, 0
	s_mov_b32 s88, -2
	v_mov_b32_e32 v3, v2
	v_mov_b32_e32 v4, v2
	v_mov_b32_e32 v5, v2
	v_mov_b32_e32 v6, v2
	v_mov_b32_e32 v7, v2
	v_mov_b32_e32 v8, v2
	v_mov_b32_e32 v9, v2
	v_mov_b32_e32 v10, v2
	v_mov_b32_e32 v11, v2
	v_mov_b32_e32 v12, v2
	v_mov_b32_e32 v13, v2
	v_mov_b32_e32 v14, v2
	v_mov_b32_e32 v15, v2
	v_mov_b32_e32 v16, v2
	v_mov_b32_e32 v17, v2
	v_mov_b32_e32 v26, v2
	v_mov_b32_e32 v27, v2
	v_mov_b32_e32 v28, v2
	v_mov_b32_e32 v29, v2
	v_mov_b32_e32 v30, v2
	v_mov_b32_e32 v31, v2
	v_mov_b32_e32 v32, v2
	v_mov_b32_e32 v33, v2
	v_mov_b32_e32 v42, v2
	v_mov_b32_e32 v43, v2
	v_mov_b32_e32 v44, v2
	v_mov_b32_e32 v45, v2
	v_mov_b32_e32 v46, v2
	v_mov_b32_e32 v47, v2
	v_mov_b32_e32 v48, v2
	v_mov_b32_e32 v49, v2
	v_mov_b32_e32 v18, v2
	v_mov_b32_e32 v19, v2
	v_mov_b32_e32 v20, v2
	v_mov_b32_e32 v21, v2
	v_mov_b32_e32 v22, v2
	v_mov_b32_e32 v23, v2
	v_mov_b32_e32 v24, v2
	v_mov_b32_e32 v25, v2
	v_mov_b32_e32 v34, v2
	v_mov_b32_e32 v35, v2
	v_mov_b32_e32 v36, v2
	v_mov_b32_e32 v37, v2
	v_mov_b32_e32 v38, v2
	v_mov_b32_e32 v39, v2
	v_mov_b32_e32 v40, v2
	v_mov_b32_e32 v41, v2
	v_mov_b32_e32 v50, v2
	v_mov_b32_e32 v51, v2
	v_mov_b32_e32 v52, v2
	v_mov_b32_e32 v53, v2
	v_mov_b32_e32 v54, v2
	v_mov_b32_e32 v55, v2
	v_mov_b32_e32 v56, v2
	v_mov_b32_e32 v57, v2
	v_mov_b32_e32 v58, v2
	v_mov_b32_e32 v59, v2
	v_mov_b32_e32 v60, v2
	v_mov_b32_e32 v61, v2
	v_mov_b32_e32 v62, v2
	v_mov_b32_e32 v63, v2
	v_mov_b32_e32 v64, v2
	v_mov_b32_e32 v65, v2
	v_mov_b32_e32 v66, v2
	v_mov_b32_e32 v67, v2
	v_mov_b32_e32 v68, v2
	v_mov_b32_e32 v69, v2
	v_mov_b32_e32 v70, v2
	v_mov_b32_e32 v71, v2
	v_mov_b32_e32 v72, v2
	v_mov_b32_e32 v73, v2
	v_mov_b32_e32 v74, v2
	v_mov_b32_e32 v75, v2
	v_mov_b32_e32 v76, v2
	v_mov_b32_e32 v77, v2
	v_mov_b32_e32 v78, v2
	v_mov_b32_e32 v79, v2
	v_mov_b32_e32 v80, v2
	v_mov_b32_e32 v81, v2
	v_mov_b32_e32 v86, v2
	v_mov_b32_e32 v87, v2
	v_mov_b32_e32 v88, v2
	v_mov_b32_e32 v89, v2
	v_mov_b32_e32 v94, v2
	v_mov_b32_e32 v95, v2
	v_mov_b32_e32 v96, v2
	v_mov_b32_e32 v97, v2
	v_mov_b32_e32 v102, v2
	v_mov_b32_e32 v103, v2
	v_mov_b32_e32 v104, v2
	v_mov_b32_e32 v105, v2
	v_mov_b32_e32 v110, v2
	v_mov_b32_e32 v111, v2
	v_mov_b32_e32 v112, v2
	v_mov_b32_e32 v113, v2
	v_mov_b32_e32 v82, v2
	v_mov_b32_e32 v83, v2
	v_mov_b32_e32 v84, v2
	v_mov_b32_e32 v85, v2
	v_mov_b32_e32 v90, v2
	v_mov_b32_e32 v91, v2
	v_mov_b32_e32 v92, v2
	v_mov_b32_e32 v93, v2
	v_mov_b32_e32 v98, v2
	v_mov_b32_e32 v99, v2
	v_mov_b32_e32 v100, v2
	v_mov_b32_e32 v101, v2
	v_mov_b32_e32 v106, v2
	v_mov_b32_e32 v107, v2
	v_mov_b32_e32 v108, v2
	v_mov_b32_e32 v109, v2
	v_mov_b32_e32 v114, v2
	v_mov_b32_e32 v115, v2
	v_mov_b32_e32 v116, v2
	v_mov_b32_e32 v117, v2
	v_mov_b32_e32 v118, v2
	v_mov_b32_e32 v119, v2
	v_mov_b32_e32 v120, v2
	v_mov_b32_e32 v121, v2
	v_mov_b32_e32 v122, v2
	v_mov_b32_e32 v123, v2
	v_mov_b32_e32 v124, v2
	v_mov_b32_e32 v125, v2
	v_mov_b32_e32 v126, v2
	v_mov_b32_e32 v127, v2
	v_mov_b32_e32 v128, v2
	v_mov_b32_e32 v129, v2
	v_readfirstlane_b32 vcc_lo, v169
	s_nop 0
	s_bitcmp1_b32 vcc_lo, 8
	s_cbranch_scc0 .Lprio_skip_cm
	s_setprio 1
.Lprio_skip_cm:
.LBB0_451:
	s_add_u32 s30, s28, 0xfffc0080
	s_addc_u32 s31, s29, -1
	s_add_i32 s89, 0, 0x10000
	s_cmp_eq_u32 s88, 12
	s_cselect_b32 s35, s21, s31
	s_cselect_b32 s34, s84, s30
	s_cselect_b32 s31, s13, s87
	s_cselect_b32 s30, s85, s86
	s_add_i32 s92, 0, 0x14000
	v_add_u32_e32 v152, s89, v137
	v_add_u32_e32 v156, s92, v137
	ds_read_b128 v[140:143], v152
	ds_read_b128 v[144:147], v152 offset:1024
	ds_read_b128 v[148:151], v152 offset:2048
	ds_read_b128 v[152:155], v152 offset:3072
	ds_read_b128 v[170:173], v156
	ds_read_b128 v[174:177], v156 offset:1024
	ds_read_b128 v[178:181], v156 offset:2048
	ds_read_b128 v[182:185], v156 offset:3072
	v_lshl_add_u64 v[156:157], s[28:29], 0, v[134:135]
	s_add_i32 m0, s67, 0xc000
	ds_read_b128 v[186:189], v139
	ds_read_b128 v[190:193], v139 offset:1024
	ds_read_b128 v[194:197], v139 offset:2048
	ds_read_b128 v[198:201], v139 offset:3072
	ds_read_b128 v[206:209], v139 offset:4096
	ds_read_b128 v[210:213], v139 offset:5120
	ds_read_b128 v[214:217], v139 offset:6144
	ds_read_b128 v[238:241], v139 offset:7168
	global_load_lds_dwordx4 v[156:157], off
	v_lshl_add_u64 v[156:157], s[28:29], 0, v[132:133]
	s_add_i32 m0, s67, 0xe000
	s_nop 0
	global_load_lds_dwordx4 v[156:157], off
	s_waitcnt vmcnt(8)
	s_waitcnt lgkmcnt(0)
	s_barrier
	s_waitcnt lgkmcnt(0)
	v_mfma_f32_16x16x32_bf16 v[126:129], v[140:143], v[186:189], v[126:129]
	v_mfma_f32_16x16x32_bf16 v[122:125], v[148:151], v[186:189], v[122:125]
	v_mfma_f32_16x16x32_bf16 v[118:121], v[140:143], v[194:197], v[118:121]
	v_mfma_f32_16x16x32_bf16 v[114:117], v[148:151], v[194:197], v[114:117]
	v_mfma_f32_16x16x32_bf16 v[106:109], v[140:143], v[206:209], v[106:109]
	v_mfma_f32_16x16x32_bf16 v[98:101], v[148:151], v[206:209], v[98:101]
	v_mfma_f32_16x16x32_bf16 v[90:93], v[140:143], v[214:217], v[90:93]
	v_mfma_f32_16x16x32_bf16 v[82:85], v[148:151], v[214:217], v[82:85]
	v_mfma_f32_16x16x32_bf16 v[126:129], v[144:147], v[190:193], v[126:129]
	v_mfma_f32_16x16x32_bf16 v[122:125], v[152:155], v[190:193], v[122:125]
	v_mfma_f32_16x16x32_bf16 v[118:121], v[144:147], v[198:201], v[118:121]
	v_mfma_f32_16x16x32_bf16 v[114:117], v[152:155], v[198:201], v[114:117]
	v_mfma_f32_16x16x32_bf16 v[106:109], v[144:147], v[210:213], v[106:109]
	v_mfma_f32_16x16x32_bf16 v[98:101], v[152:155], v[210:213], v[98:101]
	v_mfma_f32_16x16x32_bf16 v[90:93], v[144:147], v[238:241], v[90:93]
	v_mfma_f32_16x16x32_bf16 v[82:85], v[152:155], v[238:241], v[82:85]
	v_mfma_f32_16x16x32_bf16 v[110:113], v[170:173], v[186:189], v[110:113]
	v_mfma_f32_16x16x32_bf16 v[102:105], v[178:181], v[186:189], v[102:105]
	v_mfma_f32_16x16x32_bf16 v[94:97], v[170:173], v[194:197], v[94:97]
	v_mfma_f32_16x16x32_bf16 v[86:89], v[178:181], v[194:197], v[86:89]
	v_mfma_f32_16x16x32_bf16 v[78:81], v[170:173], v[206:209], v[78:81]
	v_mfma_f32_16x16x32_bf16 v[74:77], v[178:181], v[206:209], v[74:77]
	v_mfma_f32_16x16x32_bf16 v[70:73], v[170:173], v[214:217], v[70:73]
	v_mfma_f32_16x16x32_bf16 v[66:69], v[178:181], v[214:217], v[66:69]
	v_mfma_f32_16x16x32_bf16 v[110:113], v[174:177], v[190:193], v[110:113]
	v_mfma_f32_16x16x32_bf16 v[102:105], v[182:185], v[190:193], v[102:105]
	v_mfma_f32_16x16x32_bf16 v[94:97], v[174:177], v[198:201], v[94:97]
	v_mfma_f32_16x16x32_bf16 v[86:89], v[182:185], v[198:201], v[86:89]
	v_mfma_f32_16x16x32_bf16 v[78:81], v[174:177], v[210:213], v[78:81]
	v_mfma_f32_16x16x32_bf16 v[74:77], v[182:185], v[210:213], v[74:77]
	v_mfma_f32_16x16x32_bf16 v[70:73], v[174:177], v[238:241], v[70:73]
	v_mfma_f32_16x16x32_bf16 v[66:69], v[182:185], v[238:241], v[66:69]
	s_barrier
	s_add_i32 s89, s89, s66
	v_lshl_add_u64 v[156:157], s[30:31], 0, v[0:1]
	s_mov_b32 m0, s89
	ds_read_b128 v[186:189], v139 offset:16384
	ds_read_b128 v[190:193], v139 offset:17408
	ds_read_b128 v[194:197], v139 offset:18432
	ds_read_b128 v[198:201], v139 offset:19456
	ds_read_b128 v[206:209], v139 offset:20480
	ds_read_b128 v[210:213], v139 offset:21504
	ds_read_b128 v[214:217], v139 offset:22528
	ds_read_b128 v[238:241], v139 offset:23552
	global_load_lds_dwordx4 v[156:157], off
	s_add_i32 m0, s89, 0x2000
	s_add_u32 s90, s30, 0x40000
	v_lshl_add_u64 v[202:203], s[30:31], 0, v[130:131]
	s_addc_u32 s91, s31, 0
	s_add_i32 s89, s92, s66
	global_load_lds_dwordx4 v[202:203], off
	v_lshl_add_u64 v[220:221], s[90:91], 0, v[0:1]
	s_mov_b32 m0, s89
	v_lshl_add_u64 v[226:227], s[34:35], 0, v[130:131]
	global_load_lds_dwordx4 v[220:221], off
	v_lshl_add_u64 v[220:221], s[90:91], 0, v[130:131]
	s_add_i32 m0, s89, 0x2000
	s_nop 0
	global_load_lds_dwordx4 v[220:221], off
	v_lshl_add_u64 v[220:221], s[34:35], 0, v[0:1]
	s_mov_b32 m0, s67
	s_nop 0
	global_load_lds_dwordx4 v[220:221], off
	s_mov_b32 m0, s68
	s_nop 0
	global_load_lds_dwordx4 v[226:227], off
	s_waitcnt vmcnt(8)
	s_waitcnt lgkmcnt(0)
	s_barrier
	s_waitcnt lgkmcnt(0)
	v_mfma_f32_16x16x32_bf16 v[62:65], v[140:143], v[186:189], v[62:65]
	v_mfma_f32_16x16x32_bf16 v[58:61], v[148:151], v[186:189], v[58:61]
	v_mfma_f32_16x16x32_bf16 v[54:57], v[140:143], v[194:197], v[54:57]
	v_mfma_f32_16x16x32_bf16 v[50:53], v[148:151], v[194:197], v[50:53]
	v_mfma_f32_16x16x32_bf16 v[38:41], v[140:143], v[206:209], v[38:41]
	v_mfma_f32_16x16x32_bf16 v[34:37], v[148:151], v[206:209], v[34:37]
	v_mfma_f32_16x16x32_bf16 v[22:25], v[140:143], v[214:217], v[22:25]
	v_mfma_f32_16x16x32_bf16 v[18:21], v[148:151], v[214:217], v[18:21]
	v_mfma_f32_16x16x32_bf16 v[62:65], v[144:147], v[190:193], v[62:65]
	v_mfma_f32_16x16x32_bf16 v[58:61], v[152:155], v[190:193], v[58:61]
	v_mfma_f32_16x16x32_bf16 v[54:57], v[144:147], v[198:201], v[54:57]
	v_mfma_f32_16x16x32_bf16 v[50:53], v[152:155], v[198:201], v[50:53]
	v_mfma_f32_16x16x32_bf16 v[38:41], v[144:147], v[210:213], v[38:41]
	v_mfma_f32_16x16x32_bf16 v[34:37], v[152:155], v[210:213], v[34:37]
	v_mfma_f32_16x16x32_bf16 v[22:25], v[144:147], v[238:241], v[22:25]
	v_mfma_f32_16x16x32_bf16 v[18:21], v[152:155], v[238:241], v[18:21]
	v_mfma_f32_16x16x32_bf16 v[46:49], v[170:173], v[186:189], v[46:49]
	v_mfma_f32_16x16x32_bf16 v[42:45], v[178:181], v[186:189], v[42:45]
	v_mfma_f32_16x16x32_bf16 v[30:33], v[170:173], v[194:197], v[30:33]
	v_mfma_f32_16x16x32_bf16 v[26:29], v[178:181], v[194:197], v[26:29]
	v_mfma_f32_16x16x32_bf16 v[14:17], v[170:173], v[206:209], v[14:17]
	v_mfma_f32_16x16x32_bf16 v[10:13], v[178:181], v[206:209], v[10:13]
	v_mfma_f32_16x16x32_bf16 v[6:9], v[170:173], v[214:217], v[6:9]
	v_mfma_f32_16x16x32_bf16 v[2:5], v[178:181], v[214:217], v[2:5]
	v_mfma_f32_16x16x32_bf16 v[46:49], v[174:177], v[190:193], v[46:49]
	v_mfma_f32_16x16x32_bf16 v[42:45], v[182:185], v[190:193], v[42:45]
	v_mfma_f32_16x16x32_bf16 v[30:33], v[174:177], v[198:201], v[30:33]
	v_mfma_f32_16x16x32_bf16 v[26:29], v[182:185], v[198:201], v[26:29]
	v_mfma_f32_16x16x32_bf16 v[14:17], v[174:177], v[210:213], v[14:17]
	v_mfma_f32_16x16x32_bf16 v[10:13], v[182:185], v[210:213], v[10:13]
	v_mfma_f32_16x16x32_bf16 v[6:9], v[174:177], v[238:241], v[6:9]
	v_mfma_f32_16x16x32_bf16 v[2:5], v[182:185], v[238:241], v[2:5]
	s_barrier
	s_add_i32 s89, 0, 0x18000
	s_add_i32 s90, 0, 0x1c000
	v_add_u32_e32 v152, s89, v137
	v_add_u32_e32 v167, s90, v137
	ds_read_b128 v[140:143], v152
	ds_read_b128 v[144:147], v152 offset:1024
	ds_read_b128 v[148:151], v152 offset:2048
	ds_read_b128 v[152:155], v152 offset:3072
	ds_read_b128 v[170:173], v167
	ds_read_b128 v[174:177], v167 offset:1024
	ds_read_b128 v[178:181], v167 offset:2048
	ds_read_b128 v[182:185], v167 offset:3072
	s_add_u32 s34, s34, 0x40000
	s_addc_u32 s35, s35, 0
	s_mov_b32 m0, s70
	v_lshl_add_u64 v[242:243], s[34:35], 0, v[0:1]
	ds_read_b128 v[186:189], v139 offset:32768
	ds_read_b128 v[190:193], v139 offset:33792
	ds_read_b128 v[194:197], v139 offset:34816
	ds_read_b128 v[198:201], v139 offset:35840
	ds_read_b128 v[206:209], v139 offset:36864
	ds_read_b128 v[210:213], v139 offset:37888
	ds_read_b128 v[214:217], v139 offset:38912
	ds_read_b128 v[238:241], v139 offset:39936
	global_load_lds_dwordx4 v[242:243], off
	v_lshl_add_u64 v[242:243], s[34:35], 0, v[130:131]
	s_mov_b32 m0, s71
	s_nop 0
	global_load_lds_dwordx4 v[242:243], off
	s_waitcnt vmcnt(8)
	s_waitcnt lgkmcnt(0)
	s_barrier
	s_waitcnt lgkmcnt(0)
	v_mfma_f32_16x16x32_bf16 v[126:129], v[140:143], v[186:189], v[126:129]
	v_mfma_f32_16x16x32_bf16 v[122:125], v[148:151], v[186:189], v[122:125]
	v_mfma_f32_16x16x32_bf16 v[118:121], v[140:143], v[194:197], v[118:121]
	v_mfma_f32_16x16x32_bf16 v[114:117], v[148:151], v[194:197], v[114:117]
	v_mfma_f32_16x16x32_bf16 v[106:109], v[140:143], v[206:209], v[106:109]
	v_mfma_f32_16x16x32_bf16 v[98:101], v[148:151], v[206:209], v[98:101]
	v_mfma_f32_16x16x32_bf16 v[90:93], v[140:143], v[214:217], v[90:93]
	v_mfma_f32_16x16x32_bf16 v[82:85], v[148:151], v[214:217], v[82:85]
	v_mfma_f32_16x16x32_bf16 v[126:129], v[144:147], v[190:193], v[126:129]
	v_mfma_f32_16x16x32_bf16 v[122:125], v[152:155], v[190:193], v[122:125]
	v_mfma_f32_16x16x32_bf16 v[118:121], v[144:147], v[198:201], v[118:121]
	v_mfma_f32_16x16x32_bf16 v[114:117], v[152:155], v[198:201], v[114:117]
	v_mfma_f32_16x16x32_bf16 v[106:109], v[144:147], v[210:213], v[106:109]
	v_mfma_f32_16x16x32_bf16 v[98:101], v[152:155], v[210:213], v[98:101]
	v_mfma_f32_16x16x32_bf16 v[90:93], v[144:147], v[238:241], v[90:93]
	v_mfma_f32_16x16x32_bf16 v[82:85], v[152:155], v[238:241], v[82:85]
	v_mfma_f32_16x16x32_bf16 v[110:113], v[170:173], v[186:189], v[110:113]
	v_mfma_f32_16x16x32_bf16 v[102:105], v[178:181], v[186:189], v[102:105]
	v_mfma_f32_16x16x32_bf16 v[94:97], v[170:173], v[194:197], v[94:97]
	v_mfma_f32_16x16x32_bf16 v[86:89], v[178:181], v[194:197], v[86:89]
	v_mfma_f32_16x16x32_bf16 v[78:81], v[170:173], v[206:209], v[78:81]
	v_mfma_f32_16x16x32_bf16 v[74:77], v[178:181], v[206:209], v[74:77]
	v_mfma_f32_16x16x32_bf16 v[70:73], v[170:173], v[214:217], v[70:73]
	v_mfma_f32_16x16x32_bf16 v[66:69], v[178:181], v[214:217], v[66:69]
	v_mfma_f32_16x16x32_bf16 v[110:113], v[174:177], v[190:193], v[110:113]
	v_mfma_f32_16x16x32_bf16 v[102:105], v[182:185], v[190:193], v[102:105]
	v_mfma_f32_16x16x32_bf16 v[94:97], v[174:177], v[198:201], v[94:97]
	v_mfma_f32_16x16x32_bf16 v[86:89], v[182:185], v[198:201], v[86:89]
	v_mfma_f32_16x16x32_bf16 v[78:81], v[174:177], v[210:213], v[78:81]
	v_mfma_f32_16x16x32_bf16 v[74:77], v[182:185], v[210:213], v[74:77]
	v_mfma_f32_16x16x32_bf16 v[70:73], v[174:177], v[238:241], v[70:73]
	v_mfma_f32_16x16x32_bf16 v[66:69], v[182:185], v[238:241], v[66:69]
	s_barrier
	s_add_i32 s34, s89, s66
	v_lshl_add_u64 v[156:157], v[156:157], 0, s[22:23]
	s_mov_b32 m0, s34
	ds_read_b128 v[186:189], v139 offset:49152
	ds_read_b128 v[190:193], v139 offset:50176
	ds_read_b128 v[194:197], v139 offset:51200
	ds_read_b128 v[198:201], v139 offset:52224
	ds_read_b128 v[206:209], v139 offset:53248
	ds_read_b128 v[210:213], v139 offset:54272
	ds_read_b128 v[214:217], v139 offset:55296
	ds_read_b128 v[238:241], v139 offset:56320
	global_load_lds_dwordx4 v[156:157], off
	s_add_i32 m0, s34, 0x2000
	s_add_u32 s30, s30, 0x40080
	v_lshl_add_u64 v[156:157], v[202:203], 0, s[22:23]
	s_addc_u32 s31, s31, 0
	s_add_i32 s34, s90, s66
	global_load_lds_dwordx4 v[156:157], off
	v_lshl_add_u64 v[156:157], s[30:31], 0, v[0:1]
	s_mov_b32 m0, s34
	s_nop 0
	global_load_lds_dwordx4 v[156:157], off
	v_lshl_add_u64 v[156:157], s[30:31], 0, v[130:131]
	s_add_i32 m0, s34, 0x2000
	s_nop 0
	global_load_lds_dwordx4 v[156:157], off
	v_lshl_add_u64 v[156:157], v[220:221], 0, s[22:23]
	s_mov_b32 m0, s80
	s_nop 0
	global_load_lds_dwordx4 v[156:157], off
	v_lshl_add_u64 v[156:157], v[226:227], 0, s[22:23]
	s_mov_b32 m0, s81
	s_nop 0
	global_load_lds_dwordx4 v[156:157], off
	s_waitcnt vmcnt(8)
	s_waitcnt lgkmcnt(0)
	s_barrier
	s_waitcnt lgkmcnt(0)
	v_mfma_f32_16x16x32_bf16 v[62:65], v[140:143], v[186:189], v[62:65]
	v_mfma_f32_16x16x32_bf16 v[58:61], v[148:151], v[186:189], v[58:61]
	v_mfma_f32_16x16x32_bf16 v[54:57], v[140:143], v[194:197], v[54:57]
	v_mfma_f32_16x16x32_bf16 v[50:53], v[148:151], v[194:197], v[50:53]
	v_mfma_f32_16x16x32_bf16 v[38:41], v[140:143], v[206:209], v[38:41]
	v_mfma_f32_16x16x32_bf16 v[34:37], v[148:151], v[206:209], v[34:37]
	v_mfma_f32_16x16x32_bf16 v[22:25], v[140:143], v[214:217], v[22:25]
	v_mfma_f32_16x16x32_bf16 v[18:21], v[148:151], v[214:217], v[18:21]
	v_mfma_f32_16x16x32_bf16 v[62:65], v[144:147], v[190:193], v[62:65]
	v_mfma_f32_16x16x32_bf16 v[58:61], v[152:155], v[190:193], v[58:61]
	v_mfma_f32_16x16x32_bf16 v[54:57], v[144:147], v[198:201], v[54:57]
	v_mfma_f32_16x16x32_bf16 v[50:53], v[152:155], v[198:201], v[50:53]
	v_mfma_f32_16x16x32_bf16 v[38:41], v[144:147], v[210:213], v[38:41]
	v_mfma_f32_16x16x32_bf16 v[34:37], v[152:155], v[210:213], v[34:37]
	v_mfma_f32_16x16x32_bf16 v[22:25], v[144:147], v[238:241], v[22:25]
	v_mfma_f32_16x16x32_bf16 v[18:21], v[152:155], v[238:241], v[18:21]
	v_mfma_f32_16x16x32_bf16 v[46:49], v[170:173], v[186:189], v[46:49]
	v_mfma_f32_16x16x32_bf16 v[42:45], v[178:181], v[186:189], v[42:45]
	v_mfma_f32_16x16x32_bf16 v[30:33], v[170:173], v[194:197], v[30:33]
	v_mfma_f32_16x16x32_bf16 v[26:29], v[178:181], v[194:197], v[26:29]
	v_mfma_f32_16x16x32_bf16 v[14:17], v[170:173], v[206:209], v[14:17]
	v_mfma_f32_16x16x32_bf16 v[10:13], v[178:181], v[206:209], v[10:13]
	v_mfma_f32_16x16x32_bf16 v[6:9], v[170:173], v[214:217], v[6:9]
	v_mfma_f32_16x16x32_bf16 v[2:5], v[178:181], v[214:217], v[2:5]
	v_mfma_f32_16x16x32_bf16 v[46:49], v[174:177], v[190:193], v[46:49]
	v_mfma_f32_16x16x32_bf16 v[42:45], v[182:185], v[190:193], v[42:45]
	v_mfma_f32_16x16x32_bf16 v[30:33], v[174:177], v[198:201], v[30:33]
	v_mfma_f32_16x16x32_bf16 v[26:29], v[182:185], v[198:201], v[26:29]
	v_mfma_f32_16x16x32_bf16 v[14:17], v[174:177], v[210:213], v[14:17]
	v_mfma_f32_16x16x32_bf16 v[10:13], v[182:185], v[210:213], v[10:13]
	v_mfma_f32_16x16x32_bf16 v[6:9], v[174:177], v[238:241], v[6:9]
	v_mfma_f32_16x16x32_bf16 v[2:5], v[182:185], v[238:241], v[2:5]
	s_barrier
	s_add_i32 s88, s88, 2
	s_add_u32 s86, s86, 0x100
	s_addc_u32 s87, s87, 0
	s_add_u32 s28, s28, 0x100
	s_addc_u32 s29, s29, 0
	s_cmp_gt_u32 s88, 13
	s_cbranch_scc0 .LBB0_451
	s_setprio 0
	s_and_b64 vcc, exec, s[8:9]
	s_cbranch_vccz .LBB0_454
	s_barrier

.LBB0_591:
	s_ashr_i32 s77, s76, 31
	s_lshl_b64 s[8:9], s[76:77], 19
	v_readlane_b32 s26, v254, 21
	v_readlane_b32 s27, v254, 22
	s_add_u32 s78, s26, s8
	s_addc_u32 s79, s27, s9
	s_and_b64 s[8:9], s[2:3], exec
	s_cselect_b32 s1, s79, s25
	s_cselect_b32 s26, s78, s24
	s_ashr_i32 s75, s74, 31
	s_lshl_b64 s[8:9], s[74:75], 19
	v_readlane_b32 s28, v254, 39
	v_readlane_b32 s29, v254, 40
	s_add_u32 s80, s28, s8
	s_addc_u32 s81, s29, s9
	s_and_b64 s[8:9], s[2:3], exec
	s_cselect_b32 s27, s81, s5
	s_cselect_b32 s28, s80, s4
	s_add_u32 s29, s4, 0x100
	s_addc_u32 s34, s5, 0
	s_add_u32 s4, s24, 0x40080
	v_mov_b32_e32 v2, 0
	s_addc_u32 s5, s25, 0
	s_mov_b32 s35, -2
	v_mov_b32_e32 v3, v2
	v_mov_b32_e32 v4, v2
	v_mov_b32_e32 v5, v2
	v_mov_b32_e32 v6, v2
	v_mov_b32_e32 v7, v2
	v_mov_b32_e32 v8, v2
	v_mov_b32_e32 v9, v2
	v_mov_b32_e32 v18, v2
	v_mov_b32_e32 v19, v2
	v_mov_b32_e32 v20, v2
	v_mov_b32_e32 v21, v2
	v_mov_b32_e32 v22, v2
	v_mov_b32_e32 v23, v2
	v_mov_b32_e32 v24, v2
	v_mov_b32_e32 v25, v2
	v_mov_b32_e32 v34, v2
	v_mov_b32_e32 v35, v2
	v_mov_b32_e32 v36, v2
	v_mov_b32_e32 v37, v2
	v_mov_b32_e32 v38, v2
	v_mov_b32_e32 v39, v2
	v_mov_b32_e32 v40, v2
	v_mov_b32_e32 v41, v2
	v_mov_b32_e32 v50, v2
	v_mov_b32_e32 v51, v2
	v_mov_b32_e32 v52, v2
	v_mov_b32_e32 v53, v2
	v_mov_b32_e32 v54, v2
	v_mov_b32_e32 v55, v2
	v_mov_b32_e32 v56, v2
	v_mov_b32_e32 v57, v2
	v_mov_b32_e32 v10, v2
	v_mov_b32_e32 v11, v2
	v_mov_b32_e32 v12, v2
	v_mov_b32_e32 v13, v2
	v_mov_b32_e32 v14, v2
	v_mov_b32_e32 v15, v2
	v_mov_b32_e32 v16, v2
	v_mov_b32_e32 v17, v2
	v_mov_b32_e32 v26, v2
	v_mov_b32_e32 v27, v2
	v_mov_b32_e32 v28, v2
	v_mov_b32_e32 v29, v2
	v_mov_b32_e32 v30, v2
	v_mov_b32_e32 v31, v2
	v_mov_b32_e32 v32, v2
	v_mov_b32_e32 v33, v2
	v_mov_b32_e32 v42, v2
	v_mov_b32_e32 v43, v2
	v_mov_b32_e32 v44, v2
	v_mov_b32_e32 v45, v2
	v_mov_b32_e32 v46, v2
	v_mov_b32_e32 v47, v2
	v_mov_b32_e32 v48, v2
	v_mov_b32_e32 v49, v2
	v_mov_b32_e32 v58, v2
	v_mov_b32_e32 v59, v2
	v_mov_b32_e32 v60, v2
	v_mov_b32_e32 v61, v2
	v_mov_b32_e32 v62, v2
	v_mov_b32_e32 v63, v2
	v_mov_b32_e32 v64, v2
	v_mov_b32_e32 v65, v2
	v_mov_b32_e32 v66, v2
	v_mov_b32_e32 v67, v2
	v_mov_b32_e32 v68, v2
	v_mov_b32_e32 v69, v2
	v_mov_b32_e32 v70, v2
	v_mov_b32_e32 v71, v2
	v_mov_b32_e32 v72, v2
	v_mov_b32_e32 v73, v2
	v_mov_b32_e32 v82, v2
	v_mov_b32_e32 v83, v2
	v_mov_b32_e32 v84, v2
	v_mov_b32_e32 v85, v2
	v_mov_b32_e32 v86, v2
	v_mov_b32_e32 v87, v2
	v_mov_b32_e32 v88, v2
	v_mov_b32_e32 v89, v2
	v_mov_b32_e32 v98, v2
	v_mov_b32_e32 v99, v2
	v_mov_b32_e32 v100, v2
	v_mov_b32_e32 v101, v2
	v_mov_b32_e32 v102, v2
	v_mov_b32_e32 v103, v2
	v_mov_b32_e32 v104, v2
	v_mov_b32_e32 v105, v2
	v_mov_b32_e32 v114, v2
	v_mov_b32_e32 v115, v2
	v_mov_b32_e32 v116, v2
	v_mov_b32_e32 v117, v2
	v_mov_b32_e32 v118, v2
	v_mov_b32_e32 v119, v2
	v_mov_b32_e32 v120, v2
	v_mov_b32_e32 v121, v2
	v_mov_b32_e32 v74, v2
	v_mov_b32_e32 v75, v2
	v_mov_b32_e32 v76, v2
	v_mov_b32_e32 v77, v2
	v_mov_b32_e32 v78, v2
	v_mov_b32_e32 v79, v2
	v_mov_b32_e32 v80, v2
	v_mov_b32_e32 v81, v2
	v_mov_b32_e32 v90, v2
	v_mov_b32_e32 v91, v2
	v_mov_b32_e32 v92, v2
	v_mov_b32_e32 v93, v2
	v_mov_b32_e32 v94, v2
	v_mov_b32_e32 v95, v2
	v_mov_b32_e32 v96, v2
	v_mov_b32_e32 v97, v2
	v_mov_b32_e32 v106, v2
	v_mov_b32_e32 v107, v2
	v_mov_b32_e32 v108, v2
	v_mov_b32_e32 v109, v2
	v_mov_b32_e32 v110, v2
	v_mov_b32_e32 v111, v2
	v_mov_b32_e32 v112, v2
	v_mov_b32_e32 v113, v2
	v_mov_b32_e32 v122, v2
	v_mov_b32_e32 v123, v2
	v_mov_b32_e32 v124, v2
	v_mov_b32_e32 v125, v2
	v_mov_b32_e32 v126, v2
	v_mov_b32_e32 v127, v2
	v_mov_b32_e32 v128, v2
	v_mov_b32_e32 v129, v2
	v_readfirstlane_b32 vcc_lo, v169
	s_nop 0
	s_bitcmp1_b32 vcc_lo, 8
	s_cbranch_scc0 .Lprio_skip_ip
	s_setprio 1
.Lprio_skip_ip:
.LBB0_592:
	s_add_u32 s8, s4, 0xfffc0080
	s_addc_u32 s9, s5, -1
	s_add_i32 s38, 0, 0x10000
	s_cmp_eq_u32 s35, 12
	s_cselect_b32 s25, s1, s9
	s_cselect_b32 s24, s26, s8
	v_add_u32_e32 v0, s38, v189
	s_cselect_b32 s9, s27, s34
	s_cselect_b32 s8, s28, s29
	s_add_i32 s64, 0, 0x14000
	s_waitcnt lgkmcnt(0)
	ds_read_b128 v[142:145], v0
	ds_read_b128 v[146:149], v0 offset:1024
	ds_read_b128 v[150:153], v0 offset:2048
	ds_read_b128 v[154:157], v0 offset:3072
	v_add_u32_e32 v0, s64, v189
	ds_read_b128 v[170:173], v0
	ds_read_b128 v[174:177], v0 offset:1024
	ds_read_b128 v[178:181], v0 offset:2048
	ds_read_b128 v[182:185], v0 offset:3072
	v_lshl_add_u64 v[186:187], s[4:5], 0, v[140:141]
	s_add_i32 m0, s67, 0xc000
	ds_read_b128 v[194:197], v193
	ds_read_b128 v[198:201], v193 offset:1024
	ds_read_b128 v[206:209], v193 offset:2048
	ds_read_b128 v[210:213], v193 offset:3072
	ds_read_b128 v[214:217], v193 offset:4096
	ds_read_b128 v[238:241], v193 offset:5120
	ds_read_b128 v[242:245], v193 offset:6144
	ds_read_b128 v[246:249], v193 offset:7168
	global_load_lds_dwordx4 v[186:187], off
	v_lshl_add_u64 v[186:187], s[4:5], 0, v[138:139]
	s_add_i32 m0, s67, 0xe000
	s_nop 0
	global_load_lds_dwordx4 v[186:187], off
	s_waitcnt vmcnt(8)
	s_waitcnt lgkmcnt(0)
	s_barrier
	s_waitcnt lgkmcnt(0)
	v_mfma_f32_16x16x32_bf16 v[126:129], v[142:145], v[194:197], v[126:129]
	v_mfma_f32_16x16x32_bf16 v[122:125], v[150:153], v[194:197], v[122:125]
	v_mfma_f32_16x16x32_bf16 v[110:113], v[142:145], v[206:209], v[110:113]
	v_mfma_f32_16x16x32_bf16 v[106:109], v[150:153], v[206:209], v[106:109]
	v_mfma_f32_16x16x32_bf16 v[94:97], v[142:145], v[214:217], v[94:97]
	v_mfma_f32_16x16x32_bf16 v[90:93], v[150:153], v[214:217], v[90:93]
	v_mfma_f32_16x16x32_bf16 v[78:81], v[142:145], v[242:245], v[78:81]
	v_mfma_f32_16x16x32_bf16 v[74:77], v[150:153], v[242:245], v[74:77]
	v_mfma_f32_16x16x32_bf16 v[126:129], v[146:149], v[198:201], v[126:129]
	v_mfma_f32_16x16x32_bf16 v[122:125], v[154:157], v[198:201], v[122:125]
	v_mfma_f32_16x16x32_bf16 v[110:113], v[146:149], v[210:213], v[110:113]
	v_mfma_f32_16x16x32_bf16 v[106:109], v[154:157], v[210:213], v[106:109]
	v_mfma_f32_16x16x32_bf16 v[94:97], v[146:149], v[238:241], v[94:97]
	v_mfma_f32_16x16x32_bf16 v[90:93], v[154:157], v[238:241], v[90:93]
	v_mfma_f32_16x16x32_bf16 v[78:81], v[146:149], v[246:249], v[78:81]
	v_mfma_f32_16x16x32_bf16 v[74:77], v[154:157], v[246:249], v[74:77]
	v_mfma_f32_16x16x32_bf16 v[118:121], v[170:173], v[194:197], v[118:121]
	v_mfma_f32_16x16x32_bf16 v[114:117], v[178:181], v[194:197], v[114:117]
	v_mfma_f32_16x16x32_bf16 v[102:105], v[170:173], v[206:209], v[102:105]
	v_mfma_f32_16x16x32_bf16 v[98:101], v[178:181], v[206:209], v[98:101]
	v_mfma_f32_16x16x32_bf16 v[86:89], v[170:173], v[214:217], v[86:89]
	v_mfma_f32_16x16x32_bf16 v[82:85], v[178:181], v[214:217], v[82:85]
	v_mfma_f32_16x16x32_bf16 v[70:73], v[170:173], v[242:245], v[70:73]
	v_mfma_f32_16x16x32_bf16 v[66:69], v[178:181], v[242:245], v[66:69]
	v_mfma_f32_16x16x32_bf16 v[118:121], v[174:177], v[198:201], v[118:121]
	v_mfma_f32_16x16x32_bf16 v[114:117], v[182:185], v[198:201], v[114:117]
	v_mfma_f32_16x16x32_bf16 v[102:105], v[174:177], v[210:213], v[102:105]
	v_mfma_f32_16x16x32_bf16 v[98:101], v[182:185], v[210:213], v[98:101]
	v_mfma_f32_16x16x32_bf16 v[86:89], v[174:177], v[238:241], v[86:89]
	v_mfma_f32_16x16x32_bf16 v[82:85], v[182:185], v[238:241], v[82:85]
	v_mfma_f32_16x16x32_bf16 v[70:73], v[174:177], v[246:249], v[70:73]
	v_mfma_f32_16x16x32_bf16 v[66:69], v[182:185], v[246:249], v[66:69]
	s_barrier
	s_add_i32 s38, s38, s66
	v_lshl_add_u64 v[186:187], s[8:9], 0, v[132:133]
	s_mov_b32 m0, s38
	ds_read_b128 v[194:197], v193 offset:16384
	ds_read_b128 v[198:201], v193 offset:17408
	ds_read_b128 v[206:209], v193 offset:18432
	ds_read_b128 v[210:213], v193 offset:19456
	ds_read_b128 v[214:217], v193 offset:20480
	ds_read_b128 v[238:241], v193 offset:21504
	ds_read_b128 v[242:245], v193 offset:22528
	ds_read_b128 v[246:249], v193 offset:23552
	global_load_lds_dwordx4 v[186:187], off
	s_add_i32 m0, s38, 0x2000
	s_add_u32 s38, s8, 0x40000
	v_lshl_add_u64 v[202:203], s[8:9], 0, v[136:137]
	s_addc_u32 s39, s9, 0
	s_add_i32 s64, s64, s66
	global_load_lds_dwordx4 v[202:203], off
	v_lshl_add_u64 v[220:221], s[38:39], 0, v[132:133]
	s_mov_b32 m0, s64
	v_lshl_add_u64 v[250:251], s[24:25], 0, v[134:135]
	global_load_lds_dwordx4 v[220:221], off
	v_lshl_add_u64 v[220:221], s[38:39], 0, v[136:137]
	s_add_i32 m0, s64, 0x2000
	s_nop 0
	global_load_lds_dwordx4 v[220:221], off
	v_lshl_add_u64 v[220:221], s[24:25], 0, v[130:131]
	s_mov_b32 m0, s67
	s_nop 0
	global_load_lds_dwordx4 v[220:221], off
	s_mov_b32 m0, s73
	s_nop 0
	global_load_lds_dwordx4 v[250:251], off
	s_waitcnt vmcnt(8)
	s_waitcnt lgkmcnt(0)
	s_barrier
	s_waitcnt lgkmcnt(0)
	v_mfma_f32_16x16x32_bf16 v[62:65], v[142:145], v[194:197], v[62:65]
	v_mfma_f32_16x16x32_bf16 v[58:61], v[150:153], v[194:197], v[58:61]
	v_mfma_f32_16x16x32_bf16 v[46:49], v[142:145], v[206:209], v[46:49]
	v_mfma_f32_16x16x32_bf16 v[42:45], v[150:153], v[206:209], v[42:45]
	v_mfma_f32_16x16x32_bf16 v[30:33], v[142:145], v[214:217], v[30:33]
	v_mfma_f32_16x16x32_bf16 v[26:29], v[150:153], v[214:217], v[26:29]
	v_mfma_f32_16x16x32_bf16 v[14:17], v[142:145], v[242:245], v[14:17]
	v_mfma_f32_16x16x32_bf16 v[10:13], v[150:153], v[242:245], v[10:13]
	v_mfma_f32_16x16x32_bf16 v[62:65], v[146:149], v[198:201], v[62:65]
	v_mfma_f32_16x16x32_bf16 v[58:61], v[154:157], v[198:201], v[58:61]
	v_mfma_f32_16x16x32_bf16 v[46:49], v[146:149], v[210:213], v[46:49]
	v_mfma_f32_16x16x32_bf16 v[42:45], v[154:157], v[210:213], v[42:45]
	v_mfma_f32_16x16x32_bf16 v[30:33], v[146:149], v[238:241], v[30:33]
	v_mfma_f32_16x16x32_bf16 v[26:29], v[154:157], v[238:241], v[26:29]
	v_mfma_f32_16x16x32_bf16 v[14:17], v[146:149], v[246:249], v[14:17]
	v_mfma_f32_16x16x32_bf16 v[10:13], v[154:157], v[246:249], v[10:13]
	v_mfma_f32_16x16x32_bf16 v[54:57], v[170:173], v[194:197], v[54:57]
	v_mfma_f32_16x16x32_bf16 v[50:53], v[178:181], v[194:197], v[50:53]
	v_mfma_f32_16x16x32_bf16 v[38:41], v[170:173], v[206:209], v[38:41]
	v_mfma_f32_16x16x32_bf16 v[34:37], v[178:181], v[206:209], v[34:37]
	v_mfma_f32_16x16x32_bf16 v[22:25], v[170:173], v[214:217], v[22:25]
	v_mfma_f32_16x16x32_bf16 v[18:21], v[178:181], v[214:217], v[18:21]
	v_mfma_f32_16x16x32_bf16 v[6:9], v[170:173], v[242:245], v[6:9]
	v_mfma_f32_16x16x32_bf16 v[2:5], v[178:181], v[242:245], v[2:5]
	v_mfma_f32_16x16x32_bf16 v[54:57], v[174:177], v[198:201], v[54:57]
	v_mfma_f32_16x16x32_bf16 v[50:53], v[182:185], v[198:201], v[50:53]
	v_mfma_f32_16x16x32_bf16 v[38:41], v[174:177], v[210:213], v[38:41]
	v_mfma_f32_16x16x32_bf16 v[34:37], v[182:185], v[210:213], v[34:37]
	v_mfma_f32_16x16x32_bf16 v[22:25], v[174:177], v[238:241], v[22:25]
	v_mfma_f32_16x16x32_bf16 v[18:21], v[182:185], v[238:241], v[18:21]
	v_mfma_f32_16x16x32_bf16 v[6:9], v[174:177], v[246:249], v[6:9]
	v_mfma_f32_16x16x32_bf16 v[2:5], v[182:185], v[246:249], v[2:5]
	s_barrier
	s_add_i32 s38, 0, 0x18000
	v_add_u32_e32 v0, s38, v189
	s_add_i32 s39, 0, 0x1c000
	ds_read_b128 v[142:145], v0
	ds_read_b128 v[146:149], v0 offset:1024
	ds_read_b128 v[150:153], v0 offset:2048
	ds_read_b128 v[154:157], v0 offset:3072
	v_add_u32_e32 v0, s39, v189
	ds_read_b128 v[170:173], v0
	ds_read_b128 v[174:177], v0 offset:1024
	ds_read_b128 v[178:181], v0 offset:2048
	ds_read_b128 v[182:185], v0 offset:3072
	s_add_u32 s24, s24, 0x40000
	s_addc_u32 s25, s25, 0
	s_mov_b32 m0, s20
	v_lshl_add_u64 v[226:227], s[24:25], 0, v[130:131]
	ds_read_b128 v[194:197], v193 offset:32768
	ds_read_b128 v[198:201], v193 offset:33792
	ds_read_b128 v[206:209], v193 offset:34816
	ds_read_b128 v[210:213], v193 offset:35840
	ds_read_b128 v[214:217], v193 offset:36864
	ds_read_b128 v[238:241], v193 offset:37888
	ds_read_b128 v[242:245], v193 offset:38912
	ds_read_b128 v[246:249], v193 offset:39936
	global_load_lds_dwordx4 v[226:227], off
	v_lshl_add_u64 v[226:227], s[24:25], 0, v[134:135]
	s_mov_b32 m0, s21
	s_nop 0
	global_load_lds_dwordx4 v[226:227], off
	s_waitcnt vmcnt(8)
	s_waitcnt lgkmcnt(0)
	s_barrier
	s_waitcnt lgkmcnt(0)
	v_mfma_f32_16x16x32_bf16 v[126:129], v[142:145], v[194:197], v[126:129]
	v_mfma_f32_16x16x32_bf16 v[122:125], v[150:153], v[194:197], v[122:125]
	v_mfma_f32_16x16x32_bf16 v[110:113], v[142:145], v[206:209], v[110:113]
	v_mfma_f32_16x16x32_bf16 v[106:109], v[150:153], v[206:209], v[106:109]
	v_mfma_f32_16x16x32_bf16 v[94:97], v[142:145], v[214:217], v[94:97]
	v_mfma_f32_16x16x32_bf16 v[90:93], v[150:153], v[214:217], v[90:93]
	v_mfma_f32_16x16x32_bf16 v[78:81], v[142:145], v[242:245], v[78:81]
	v_mfma_f32_16x16x32_bf16 v[74:77], v[150:153], v[242:245], v[74:77]
	v_mfma_f32_16x16x32_bf16 v[126:129], v[146:149], v[198:201], v[126:129]
	v_mfma_f32_16x16x32_bf16 v[122:125], v[154:157], v[198:201], v[122:125]
	v_mfma_f32_16x16x32_bf16 v[110:113], v[146:149], v[210:213], v[110:113]
	v_mfma_f32_16x16x32_bf16 v[106:109], v[154:157], v[210:213], v[106:109]
	v_mfma_f32_16x16x32_bf16 v[94:97], v[146:149], v[238:241], v[94:97]
	v_mfma_f32_16x16x32_bf16 v[90:93], v[154:157], v[238:241], v[90:93]
	v_mfma_f32_16x16x32_bf16 v[78:81], v[146:149], v[246:249], v[78:81]
	v_mfma_f32_16x16x32_bf16 v[74:77], v[154:157], v[246:249], v[74:77]
	v_mfma_f32_16x16x32_bf16 v[118:121], v[170:173], v[194:197], v[118:121]
	v_mfma_f32_16x16x32_bf16 v[114:117], v[178:181], v[194:197], v[114:117]
	v_mfma_f32_16x16x32_bf16 v[102:105], v[170:173], v[206:209], v[102:105]
	v_mfma_f32_16x16x32_bf16 v[98:101], v[178:181], v[206:209], v[98:101]
	v_mfma_f32_16x16x32_bf16 v[86:89], v[170:173], v[214:217], v[86:89]
	v_mfma_f32_16x16x32_bf16 v[82:85], v[178:181], v[214:217], v[82:85]
	v_mfma_f32_16x16x32_bf16 v[70:73], v[170:173], v[242:245], v[70:73]
	v_mfma_f32_16x16x32_bf16 v[66:69], v[178:181], v[242:245], v[66:69]
	v_mfma_f32_16x16x32_bf16 v[118:121], v[174:177], v[198:201], v[118:121]
	v_mfma_f32_16x16x32_bf16 v[114:117], v[182:185], v[198:201], v[114:117]
	v_mfma_f32_16x16x32_bf16 v[102:105], v[174:177], v[210:213], v[102:105]
	v_mfma_f32_16x16x32_bf16 v[98:101], v[182:185], v[210:213], v[98:101]
	v_mfma_f32_16x16x32_bf16 v[86:89], v[174:177], v[238:241], v[86:89]
	v_mfma_f32_16x16x32_bf16 v[82:85], v[182:185], v[238:241], v[82:85]
	v_mfma_f32_16x16x32_bf16 v[70:73], v[174:177], v[246:249], v[70:73]
	v_mfma_f32_16x16x32_bf16 v[66:69], v[182:185], v[246:249], v[66:69]
	s_barrier
	s_add_i32 s24, s38, s66
	v_lshl_add_u64 v[186:187], v[186:187], 0, s[22:23]
	s_mov_b32 m0, s24
	ds_read_b128 v[194:197], v193 offset:49152
	ds_read_b128 v[198:201], v193 offset:50176
	ds_read_b128 v[206:209], v193 offset:51200
	ds_read_b128 v[210:213], v193 offset:52224
	ds_read_b128 v[214:217], v193 offset:53248
	ds_read_b128 v[238:241], v193 offset:54272
	ds_read_b128 v[242:245], v193 offset:55296
	ds_read_b128 v[246:249], v193 offset:56320
	global_load_lds_dwordx4 v[186:187], off
	s_add_i32 m0, s24, 0x2000
	s_add_u32 s8, s8, 0x40080
	v_lshl_add_u64 v[186:187], v[202:203], 0, s[22:23]
	s_addc_u32 s9, s9, 0
	s_add_i32 s24, s39, s66
	global_load_lds_dwordx4 v[186:187], off
	v_lshl_add_u64 v[186:187], s[8:9], 0, v[132:133]
	s_mov_b32 m0, s24
	s_nop 0
	global_load_lds_dwordx4 v[186:187], off
	v_lshl_add_u64 v[186:187], s[8:9], 0, v[136:137]
	s_add_i32 m0, s24, 0x2000
	s_nop 0
	global_load_lds_dwordx4 v[186:187], off
	v_lshl_add_u64 v[186:187], v[220:221], 0, s[22:23]
	s_mov_b32 m0, s6
	s_nop 0
	global_load_lds_dwordx4 v[186:187], off
	v_lshl_add_u64 v[186:187], v[250:251], 0, s[22:23]
	s_mov_b32 m0, s7
	s_nop 0
	global_load_lds_dwordx4 v[186:187], off
	s_waitcnt vmcnt(8)
	s_waitcnt lgkmcnt(0)
	s_barrier
	s_waitcnt lgkmcnt(0)
	v_mfma_f32_16x16x32_bf16 v[62:65], v[142:145], v[194:197], v[62:65]
	v_mfma_f32_16x16x32_bf16 v[58:61], v[150:153], v[194:197], v[58:61]
	v_mfma_f32_16x16x32_bf16 v[46:49], v[142:145], v[206:209], v[46:49]
	v_mfma_f32_16x16x32_bf16 v[42:45], v[150:153], v[206:209], v[42:45]
	v_mfma_f32_16x16x32_bf16 v[30:33], v[142:145], v[214:217], v[30:33]
	v_mfma_f32_16x16x32_bf16 v[26:29], v[150:153], v[214:217], v[26:29]
	v_mfma_f32_16x16x32_bf16 v[14:17], v[142:145], v[242:245], v[14:17]
	v_mfma_f32_16x16x32_bf16 v[10:13], v[150:153], v[242:245], v[10:13]
	v_mfma_f32_16x16x32_bf16 v[62:65], v[146:149], v[198:201], v[62:65]
	v_mfma_f32_16x16x32_bf16 v[58:61], v[154:157], v[198:201], v[58:61]
	v_mfma_f32_16x16x32_bf16 v[46:49], v[146:149], v[210:213], v[46:49]
	v_mfma_f32_16x16x32_bf16 v[42:45], v[154:157], v[210:213], v[42:45]
	v_mfma_f32_16x16x32_bf16 v[30:33], v[146:149], v[238:241], v[30:33]
	v_mfma_f32_16x16x32_bf16 v[26:29], v[154:157], v[238:241], v[26:29]
	v_mfma_f32_16x16x32_bf16 v[14:17], v[146:149], v[246:249], v[14:17]
	v_mfma_f32_16x16x32_bf16 v[10:13], v[154:157], v[246:249], v[10:13]
	v_mfma_f32_16x16x32_bf16 v[54:57], v[170:173], v[194:197], v[54:57]
	v_mfma_f32_16x16x32_bf16 v[50:53], v[178:181], v[194:197], v[50:53]
	v_mfma_f32_16x16x32_bf16 v[38:41], v[170:173], v[206:209], v[38:41]
	v_mfma_f32_16x16x32_bf16 v[34:37], v[178:181], v[206:209], v[34:37]
	v_mfma_f32_16x16x32_bf16 v[22:25], v[170:173], v[214:217], v[22:25]
	v_mfma_f32_16x16x32_bf16 v[18:21], v[178:181], v[214:217], v[18:21]
	v_mfma_f32_16x16x32_bf16 v[6:9], v[170:173], v[242:245], v[6:9]
	v_mfma_f32_16x16x32_bf16 v[2:5], v[178:181], v[242:245], v[2:5]
	v_mfma_f32_16x16x32_bf16 v[54:57], v[174:177], v[198:201], v[54:57]
	v_mfma_f32_16x16x32_bf16 v[50:53], v[182:185], v[198:201], v[50:53]
	v_mfma_f32_16x16x32_bf16 v[38:41], v[174:177], v[210:213], v[38:41]
	v_mfma_f32_16x16x32_bf16 v[34:37], v[182:185], v[210:213], v[34:37]
	v_mfma_f32_16x16x32_bf16 v[22:25], v[174:177], v[238:241], v[22:25]
	v_mfma_f32_16x16x32_bf16 v[18:21], v[182:185], v[238:241], v[18:21]
	v_mfma_f32_16x16x32_bf16 v[6:9], v[174:177], v[246:249], v[6:9]
	v_mfma_f32_16x16x32_bf16 v[2:5], v[182:185], v[246:249], v[2:5]
	s_barrier
	s_add_i32 s35, s35, 2
	s_add_u32 s29, s29, 0x100
	s_addc_u32 s34, s34, 0
	s_add_u32 s4, s4, 0x100
	s_addc_u32 s5, s5, 0
	s_cmp_gt_u32 s35, 13
	s_cbranch_scc0 .LBB0_592
	s_setprio 0
	v_readlane_b32 s4, v254, 44
	v_readlane_b32 s5, v254, 45
	s_and_b64 vcc, exec, s[4:5]
	s_cbranch_vccz .LBB0_595
	s_barrier

.LBB0_899:
	s_add_u32 s71, s24, 0x100
	v_mov_b32_e32 v2, 0
	s_addc_u32 s72, s25, 0
	s_mov_b32 s73, -2
	s_waitcnt lgkmcnt(0)
	v_mov_b32_e32 v3, v2
	v_mov_b32_e32 v4, v2
	v_mov_b32_e32 v5, v2
	v_mov_b32_e32 v6, v2
	v_mov_b32_e32 v7, v2
	v_mov_b32_e32 v8, v2
	v_mov_b32_e32 v9, v2
	v_mov_b32_e32 v18, v2
	v_mov_b32_e32 v19, v2
	v_mov_b32_e32 v20, v2
	v_mov_b32_e32 v21, v2
	v_mov_b32_e32 v22, v2
	v_mov_b32_e32 v23, v2
	v_mov_b32_e32 v24, v2
	v_mov_b32_e32 v25, v2
	v_mov_b32_e32 v34, v2
	v_mov_b32_e32 v35, v2
	v_mov_b32_e32 v36, v2
	v_mov_b32_e32 v37, v2
	v_mov_b32_e32 v38, v2
	v_mov_b32_e32 v39, v2
	v_mov_b32_e32 v40, v2
	v_mov_b32_e32 v41, v2
	s_waitcnt lgkmcnt(0)
	v_mov_b32_e32 v50, v2
	v_mov_b32_e32 v51, v2
	v_mov_b32_e32 v52, v2
	v_mov_b32_e32 v53, v2
	v_mov_b32_e32 v54, v2
	v_mov_b32_e32 v55, v2
	v_mov_b32_e32 v56, v2
	v_mov_b32_e32 v57, v2
	v_mov_b32_e32 v10, v2
	v_mov_b32_e32 v11, v2
	v_mov_b32_e32 v12, v2
	v_mov_b32_e32 v13, v2
	v_mov_b32_e32 v14, v2
	v_mov_b32_e32 v15, v2
	v_mov_b32_e32 v16, v2
	v_mov_b32_e32 v17, v2
	v_mov_b32_e32 v26, v2
	v_mov_b32_e32 v27, v2
	v_mov_b32_e32 v28, v2
	v_mov_b32_e32 v29, v2
	v_mov_b32_e32 v30, v2
	v_mov_b32_e32 v31, v2
	v_mov_b32_e32 v32, v2
	v_mov_b32_e32 v33, v2
	v_mov_b32_e32 v42, v2
	v_mov_b32_e32 v43, v2
	v_mov_b32_e32 v44, v2
	v_mov_b32_e32 v45, v2
	v_mov_b32_e32 v46, v2
	v_mov_b32_e32 v47, v2
	v_mov_b32_e32 v48, v2
	v_mov_b32_e32 v49, v2
	v_mov_b32_e32 v58, v2
	v_mov_b32_e32 v59, v2
	v_mov_b32_e32 v60, v2
	v_mov_b32_e32 v61, v2
	v_mov_b32_e32 v62, v2
	v_mov_b32_e32 v63, v2
	v_mov_b32_e32 v64, v2
	v_mov_b32_e32 v65, v2
	v_mov_b32_e32 v66, v2
	v_mov_b32_e32 v67, v2
	v_mov_b32_e32 v68, v2
	v_mov_b32_e32 v69, v2
	v_mov_b32_e32 v70, v2
	v_mov_b32_e32 v71, v2
	v_mov_b32_e32 v72, v2
	v_mov_b32_e32 v73, v2
	v_mov_b32_e32 v82, v2
	v_mov_b32_e32 v83, v2
	v_mov_b32_e32 v84, v2
	v_mov_b32_e32 v85, v2
	v_mov_b32_e32 v86, v2
	v_mov_b32_e32 v87, v2
	v_mov_b32_e32 v88, v2
	v_mov_b32_e32 v89, v2
	v_mov_b32_e32 v98, v2
	v_mov_b32_e32 v99, v2
	v_mov_b32_e32 v100, v2
	v_mov_b32_e32 v101, v2
	v_mov_b32_e32 v102, v2
	v_mov_b32_e32 v103, v2
	v_mov_b32_e32 v104, v2
	v_mov_b32_e32 v105, v2
	v_mov_b32_e32 v114, v2
	v_mov_b32_e32 v115, v2
	v_mov_b32_e32 v116, v2
	v_mov_b32_e32 v117, v2
	v_mov_b32_e32 v118, v2
	v_mov_b32_e32 v119, v2
	v_mov_b32_e32 v120, v2
	v_mov_b32_e32 v121, v2
	v_mov_b32_e32 v74, v2
	v_mov_b32_e32 v75, v2
	v_mov_b32_e32 v76, v2
	v_mov_b32_e32 v77, v2
	v_mov_b32_e32 v78, v2
	v_mov_b32_e32 v79, v2
	v_mov_b32_e32 v80, v2
	v_mov_b32_e32 v81, v2
	v_mov_b32_e32 v90, v2
	v_mov_b32_e32 v91, v2
	v_mov_b32_e32 v92, v2
	v_mov_b32_e32 v93, v2
	v_mov_b32_e32 v94, v2
	v_mov_b32_e32 v95, v2
	v_mov_b32_e32 v96, v2
	v_mov_b32_e32 v97, v2
	v_mov_b32_e32 v106, v2
	v_mov_b32_e32 v107, v2
	v_mov_b32_e32 v108, v2
	v_mov_b32_e32 v109, v2
	v_mov_b32_e32 v110, v2
	v_mov_b32_e32 v111, v2
	v_mov_b32_e32 v112, v2
	v_mov_b32_e32 v113, v2
	v_mov_b32_e32 v122, v2
	v_mov_b32_e32 v123, v2
	v_mov_b32_e32 v124, v2
	v_mov_b32_e32 v125, v2
	v_mov_b32_e32 v126, v2
	v_mov_b32_e32 v127, v2
	v_mov_b32_e32 v128, v2
	v_mov_b32_e32 v129, v2
	v_readfirstlane_b32 vcc_lo, v169
	s_nop 0
	s_bitcmp1_b32 vcc_lo, 8
	s_cbranch_scc0 .Lprio_skip_dn
	s_setprio 1
.Lprio_skip_dn:
.LBB0_900:
	s_add_u32 s24, s20, 0x100
	s_addc_u32 s25, s21, 0
	s_add_i32 s74, 0, 0x10000
	s_cmp_eq_u32 s73, 40
	s_cselect_b32 s29, s1, s25
	s_cselect_b32 s28, s0, s24
	v_add_u32_e32 v156, s74, v145
	s_cselect_b32 s27, s17, s72
	s_cselect_b32 s26, s16, s71
	s_add_i32 s75, 0, 0x14000
	ds_read_b128 v[140:143], v156
	ds_read_b128 v[148:151], v156 offset:1024
	ds_read_b128 v[152:155], v156 offset:2048
	ds_read_b128 v[170:173], v156 offset:3072
	v_add_u32_e32 v156, s75, v145
	ds_read_b128 v[174:177], v156
	ds_read_b128 v[178:181], v156 offset:1024
	ds_read_b128 v[182:185], v156 offset:2048
	ds_read_b128 v[186:189], v156 offset:3072
	v_lshl_add_u64 v[156:157], s[20:21], 0, v[138:139]
	s_add_i32 m0, s31, 0xc000
	ds_read_b128 v[190:193], v147
	ds_read_b128 v[194:197], v147 offset:1024
	ds_read_b128 v[198:201], v147 offset:2048
	ds_read_b128 v[206:209], v147 offset:3072
	ds_read_b128 v[210:213], v147 offset:4096
	ds_read_b128 v[214:217], v147 offset:5120
	ds_read_b128 v[238:241], v147 offset:6144
	ds_read_b128 v[242:245], v147 offset:7168
	global_load_lds_dwordx4 v[156:157], off
	v_lshl_add_u64 v[156:157], s[20:21], 0, v[136:137]
	s_add_i32 m0, s31, 0xe000
	s_nop 0
	global_load_lds_dwordx4 v[156:157], off
	s_waitcnt vmcnt(8)
	s_waitcnt lgkmcnt(0)
	s_barrier
	s_waitcnt lgkmcnt(0)
	v_mfma_f32_16x16x32_bf16 v[126:129], v[140:143], v[190:193], v[126:129]
	v_mfma_f32_16x16x32_bf16 v[122:125], v[152:155], v[190:193], v[122:125]
	v_mfma_f32_16x16x32_bf16 v[110:113], v[140:143], v[198:201], v[110:113]
	v_mfma_f32_16x16x32_bf16 v[106:109], v[152:155], v[198:201], v[106:109]
	v_mfma_f32_16x16x32_bf16 v[94:97], v[140:143], v[210:213], v[94:97]
	v_mfma_f32_16x16x32_bf16 v[90:93], v[152:155], v[210:213], v[90:93]
	v_mfma_f32_16x16x32_bf16 v[78:81], v[140:143], v[238:241], v[78:81]
	v_mfma_f32_16x16x32_bf16 v[74:77], v[152:155], v[238:241], v[74:77]
	v_mfma_f32_16x16x32_bf16 v[126:129], v[148:151], v[194:197], v[126:129]
	v_mfma_f32_16x16x32_bf16 v[122:125], v[170:173], v[194:197], v[122:125]
	v_mfma_f32_16x16x32_bf16 v[110:113], v[148:151], v[206:209], v[110:113]
	v_mfma_f32_16x16x32_bf16 v[106:109], v[170:173], v[206:209], v[106:109]
	v_mfma_f32_16x16x32_bf16 v[94:97], v[148:151], v[214:217], v[94:97]
	v_mfma_f32_16x16x32_bf16 v[90:93], v[170:173], v[214:217], v[90:93]
	v_mfma_f32_16x16x32_bf16 v[78:81], v[148:151], v[242:245], v[78:81]
	v_mfma_f32_16x16x32_bf16 v[74:77], v[170:173], v[242:245], v[74:77]
	v_mfma_f32_16x16x32_bf16 v[118:121], v[174:177], v[190:193], v[118:121]
	v_mfma_f32_16x16x32_bf16 v[114:117], v[182:185], v[190:193], v[114:117]
	v_mfma_f32_16x16x32_bf16 v[102:105], v[174:177], v[198:201], v[102:105]
	v_mfma_f32_16x16x32_bf16 v[98:101], v[182:185], v[198:201], v[98:101]
	v_mfma_f32_16x16x32_bf16 v[86:89], v[174:177], v[210:213], v[86:89]
	v_mfma_f32_16x16x32_bf16 v[82:85], v[182:185], v[210:213], v[82:85]
	v_mfma_f32_16x16x32_bf16 v[70:73], v[174:177], v[238:241], v[70:73]
	v_mfma_f32_16x16x32_bf16 v[66:69], v[182:185], v[238:241], v[66:69]
	v_mfma_f32_16x16x32_bf16 v[118:121], v[178:181], v[194:197], v[118:121]
	v_mfma_f32_16x16x32_bf16 v[114:117], v[186:189], v[194:197], v[114:117]
	v_mfma_f32_16x16x32_bf16 v[102:105], v[178:181], v[206:209], v[102:105]
	v_mfma_f32_16x16x32_bf16 v[98:101], v[186:189], v[206:209], v[98:101]
	v_mfma_f32_16x16x32_bf16 v[86:89], v[178:181], v[214:217], v[86:89]
	v_mfma_f32_16x16x32_bf16 v[82:85], v[186:189], v[214:217], v[82:85]
	v_mfma_f32_16x16x32_bf16 v[70:73], v[178:181], v[242:245], v[70:73]
	v_mfma_f32_16x16x32_bf16 v[66:69], v[186:189], v[242:245], v[66:69]
	s_barrier
	s_add_i32 s20, s74, s18
	v_lshl_add_u64 v[156:157], s[26:27], 0, v[0:1]
	s_mov_b32 m0, s20
	ds_read_b128 v[190:193], v147 offset:16384
	ds_read_b128 v[194:197], v147 offset:17408
	ds_read_b128 v[198:201], v147 offset:18432
	ds_read_b128 v[206:209], v147 offset:19456
	ds_read_b128 v[210:213], v147 offset:20480
	ds_read_b128 v[214:217], v147 offset:21504
	ds_read_b128 v[238:241], v147 offset:22528
	ds_read_b128 v[242:245], v147 offset:23552
	global_load_lds_dwordx4 v[156:157], off
	s_add_i32 m0, s20, 0x2000
	s_add_u32 s20, s26, 0xb0000
	v_lshl_add_u64 v[202:203], s[26:27], 0, v[134:135]
	s_addc_u32 s21, s27, 0
	s_add_i32 s74, s75, s18
	global_load_lds_dwordx4 v[202:203], off
	v_lshl_add_u64 v[220:221], s[20:21], 0, v[0:1]
	s_mov_b32 m0, s74
	v_lshl_add_u64 v[246:247], s[28:29], 0, v[132:133]
	global_load_lds_dwordx4 v[220:221], off
	v_lshl_add_u64 v[220:221], s[20:21], 0, v[134:135]
	s_add_i32 m0, s74, 0x2000
	s_nop 0
	global_load_lds_dwordx4 v[220:221], off
	v_lshl_add_u64 v[220:221], s[28:29], 0, v[130:131]
	s_mov_b32 m0, s31
	s_nop 0
	global_load_lds_dwordx4 v[220:221], off
	s_mov_b32 m0, s34
	s_nop 0
	global_load_lds_dwordx4 v[246:247], off
	s_waitcnt vmcnt(8)
	s_waitcnt lgkmcnt(0)
	s_barrier
	s_waitcnt lgkmcnt(0)
	v_mfma_f32_16x16x32_bf16 v[62:65], v[140:143], v[190:193], v[62:65]
	v_mfma_f32_16x16x32_bf16 v[58:61], v[152:155], v[190:193], v[58:61]
	v_mfma_f32_16x16x32_bf16 v[46:49], v[140:143], v[198:201], v[46:49]
	v_mfma_f32_16x16x32_bf16 v[42:45], v[152:155], v[198:201], v[42:45]
	v_mfma_f32_16x16x32_bf16 v[30:33], v[140:143], v[210:213], v[30:33]
	v_mfma_f32_16x16x32_bf16 v[26:29], v[152:155], v[210:213], v[26:29]
	v_mfma_f32_16x16x32_bf16 v[14:17], v[140:143], v[238:241], v[14:17]
	v_mfma_f32_16x16x32_bf16 v[10:13], v[152:155], v[238:241], v[10:13]
	v_mfma_f32_16x16x32_bf16 v[62:65], v[148:151], v[194:197], v[62:65]
	v_mfma_f32_16x16x32_bf16 v[58:61], v[170:173], v[194:197], v[58:61]
	v_mfma_f32_16x16x32_bf16 v[46:49], v[148:151], v[206:209], v[46:49]
	v_mfma_f32_16x16x32_bf16 v[42:45], v[170:173], v[206:209], v[42:45]
	v_mfma_f32_16x16x32_bf16 v[30:33], v[148:151], v[214:217], v[30:33]
	v_mfma_f32_16x16x32_bf16 v[26:29], v[170:173], v[214:217], v[26:29]
	v_mfma_f32_16x16x32_bf16 v[14:17], v[148:151], v[242:245], v[14:17]
	v_mfma_f32_16x16x32_bf16 v[10:13], v[170:173], v[242:245], v[10:13]
	v_mfma_f32_16x16x32_bf16 v[54:57], v[174:177], v[190:193], v[54:57]
	v_mfma_f32_16x16x32_bf16 v[50:53], v[182:185], v[190:193], v[50:53]
	v_mfma_f32_16x16x32_bf16 v[38:41], v[174:177], v[198:201], v[38:41]
	v_mfma_f32_16x16x32_bf16 v[34:37], v[182:185], v[198:201], v[34:37]
	v_mfma_f32_16x16x32_bf16 v[22:25], v[174:177], v[210:213], v[22:25]
	v_mfma_f32_16x16x32_bf16 v[18:21], v[182:185], v[210:213], v[18:21]
	v_mfma_f32_16x16x32_bf16 v[6:9], v[174:177], v[238:241], v[6:9]
	v_mfma_f32_16x16x32_bf16 v[2:5], v[182:185], v[238:241], v[2:5]
	v_mfma_f32_16x16x32_bf16 v[54:57], v[178:181], v[194:197], v[54:57]
	v_mfma_f32_16x16x32_bf16 v[50:53], v[186:189], v[194:197], v[50:53]
	v_mfma_f32_16x16x32_bf16 v[38:41], v[178:181], v[206:209], v[38:41]
	v_mfma_f32_16x16x32_bf16 v[34:37], v[186:189], v[206:209], v[34:37]
	v_mfma_f32_16x16x32_bf16 v[22:25], v[178:181], v[214:217], v[22:25]
	v_mfma_f32_16x16x32_bf16 v[18:21], v[186:189], v[214:217], v[18:21]
	v_mfma_f32_16x16x32_bf16 v[6:9], v[178:181], v[242:245], v[6:9]
	v_mfma_f32_16x16x32_bf16 v[2:5], v[186:189], v[242:245], v[2:5]
	s_barrier
	s_add_i32 s74, 0, 0x18000
	v_add_u32_e32 v167, s74, v145
	s_add_i32 s75, 0, 0x1c000
	ds_read_b128 v[140:143], v167
	ds_read_b128 v[148:151], v167 offset:1024
	ds_read_b128 v[152:155], v167 offset:2048
	ds_read_b128 v[170:173], v167 offset:3072
	v_add_u32_e32 v167, s75, v145
	ds_read_b128 v[174:177], v167
	ds_read_b128 v[178:181], v167 offset:1024
	ds_read_b128 v[182:185], v167 offset:2048
	ds_read_b128 v[186:189], v167 offset:3072
	s_add_u32 s20, s28, 0xb0000
	s_addc_u32 s21, s29, 0
	s_mov_b32 m0, s35
	v_lshl_add_u64 v[248:249], s[20:21], 0, v[130:131]
	ds_read_b128 v[190:193], v147 offset:32768
	ds_read_b128 v[194:197], v147 offset:33792
	ds_read_b128 v[198:201], v147 offset:34816
	ds_read_b128 v[206:209], v147 offset:35840
	ds_read_b128 v[210:213], v147 offset:36864
	ds_read_b128 v[214:217], v147 offset:37888
	ds_read_b128 v[238:241], v147 offset:38912
	ds_read_b128 v[242:245], v147 offset:39936
	global_load_lds_dwordx4 v[248:249], off
	v_lshl_add_u64 v[248:249], s[20:21], 0, v[132:133]
	s_mov_b32 m0, s38
	s_nop 0
	global_load_lds_dwordx4 v[248:249], off
	s_waitcnt vmcnt(8)
	s_waitcnt lgkmcnt(0)
	s_barrier
	s_waitcnt lgkmcnt(0)
	v_mfma_f32_16x16x32_bf16 v[126:129], v[140:143], v[190:193], v[126:129]
	v_mfma_f32_16x16x32_bf16 v[122:125], v[152:155], v[190:193], v[122:125]
	v_mfma_f32_16x16x32_bf16 v[110:113], v[140:143], v[198:201], v[110:113]
	v_mfma_f32_16x16x32_bf16 v[106:109], v[152:155], v[198:201], v[106:109]
	v_mfma_f32_16x16x32_bf16 v[94:97], v[140:143], v[210:213], v[94:97]
	v_mfma_f32_16x16x32_bf16 v[90:93], v[152:155], v[210:213], v[90:93]
	v_mfma_f32_16x16x32_bf16 v[78:81], v[140:143], v[238:241], v[78:81]
	v_mfma_f32_16x16x32_bf16 v[74:77], v[152:155], v[238:241], v[74:77]
	v_mfma_f32_16x16x32_bf16 v[126:129], v[148:151], v[194:197], v[126:129]
	v_mfma_f32_16x16x32_bf16 v[122:125], v[170:173], v[194:197], v[122:125]
	v_mfma_f32_16x16x32_bf16 v[110:113], v[148:151], v[206:209], v[110:113]
	v_mfma_f32_16x16x32_bf16 v[106:109], v[170:173], v[206:209], v[106:109]
	v_mfma_f32_16x16x32_bf16 v[94:97], v[148:151], v[214:217], v[94:97]
	v_mfma_f32_16x16x32_bf16 v[90:93], v[170:173], v[214:217], v[90:93]
	v_mfma_f32_16x16x32_bf16 v[78:81], v[148:151], v[242:245], v[78:81]
	v_mfma_f32_16x16x32_bf16 v[74:77], v[170:173], v[242:245], v[74:77]
	v_mfma_f32_16x16x32_bf16 v[118:121], v[174:177], v[190:193], v[118:121]
	v_mfma_f32_16x16x32_bf16 v[114:117], v[182:185], v[190:193], v[114:117]
	v_mfma_f32_16x16x32_bf16 v[102:105], v[174:177], v[198:201], v[102:105]
	v_mfma_f32_16x16x32_bf16 v[98:101], v[182:185], v[198:201], v[98:101]
	v_mfma_f32_16x16x32_bf16 v[86:89], v[174:177], v[210:213], v[86:89]
	v_mfma_f32_16x16x32_bf16 v[82:85], v[182:185], v[210:213], v[82:85]
	v_mfma_f32_16x16x32_bf16 v[70:73], v[174:177], v[238:241], v[70:73]
	v_mfma_f32_16x16x32_bf16 v[66:69], v[182:185], v[238:241], v[66:69]
	v_mfma_f32_16x16x32_bf16 v[118:121], v[178:181], v[194:197], v[118:121]
	v_mfma_f32_16x16x32_bf16 v[114:117], v[186:189], v[194:197], v[114:117]
	v_mfma_f32_16x16x32_bf16 v[102:105], v[178:181], v[206:209], v[102:105]
	v_mfma_f32_16x16x32_bf16 v[98:101], v[186:189], v[206:209], v[98:101]
	v_mfma_f32_16x16x32_bf16 v[86:89], v[178:181], v[214:217], v[86:89]
	v_mfma_f32_16x16x32_bf16 v[82:85], v[186:189], v[214:217], v[82:85]
	v_mfma_f32_16x16x32_bf16 v[70:73], v[178:181], v[242:245], v[70:73]
	v_mfma_f32_16x16x32_bf16 v[66:69], v[186:189], v[242:245], v[66:69]
	s_barrier
	s_add_i32 s20, s74, s18
	v_lshl_add_u64 v[156:157], v[156:157], 0, s[22:23]
	s_mov_b32 m0, s20
	ds_read_b128 v[190:193], v147 offset:49152
	ds_read_b128 v[194:197], v147 offset:50176
	ds_read_b128 v[198:201], v147 offset:51200
	ds_read_b128 v[206:209], v147 offset:52224
	ds_read_b128 v[210:213], v147 offset:53248
	ds_read_b128 v[214:217], v147 offset:54272
	ds_read_b128 v[238:241], v147 offset:55296
	ds_read_b128 v[242:245], v147 offset:56320
	global_load_lds_dwordx4 v[156:157], off
	s_add_i32 m0, s20, 0x2000
	s_add_u32 s20, s26, 0xb0080
	v_lshl_add_u64 v[156:157], v[202:203], 0, s[22:23]
	s_addc_u32 s21, s27, 0
	s_add_i32 s26, s75, s18
	global_load_lds_dwordx4 v[156:157], off
	v_lshl_add_u64 v[156:157], s[20:21], 0, v[0:1]
	s_mov_b32 m0, s26
	s_nop 0
	global_load_lds_dwordx4 v[156:157], off
	v_lshl_add_u64 v[156:157], s[20:21], 0, v[134:135]
	s_add_i32 m0, s26, 0x2000
	s_nop 0
	global_load_lds_dwordx4 v[156:157], off
	v_lshl_add_u64 v[156:157], v[220:221], 0, s[22:23]
	s_mov_b32 m0, s61
	s_nop 0
	global_load_lds_dwordx4 v[156:157], off
	v_lshl_add_u64 v[156:157], v[246:247], 0, s[22:23]
	s_mov_b32 m0, s64
	s_nop 0
	global_load_lds_dwordx4 v[156:157], off
	s_waitcnt vmcnt(8)
	s_waitcnt lgkmcnt(0)
	s_barrier
	s_waitcnt lgkmcnt(0)
	v_mfma_f32_16x16x32_bf16 v[62:65], v[140:143], v[190:193], v[62:65]
	v_mfma_f32_16x16x32_bf16 v[58:61], v[152:155], v[190:193], v[58:61]
	v_mfma_f32_16x16x32_bf16 v[46:49], v[140:143], v[198:201], v[46:49]
	v_mfma_f32_16x16x32_bf16 v[42:45], v[152:155], v[198:201], v[42:45]
	v_mfma_f32_16x16x32_bf16 v[30:33], v[140:143], v[210:213], v[30:33]
	v_mfma_f32_16x16x32_bf16 v[26:29], v[152:155], v[210:213], v[26:29]
	v_mfma_f32_16x16x32_bf16 v[14:17], v[140:143], v[238:241], v[14:17]
	v_mfma_f32_16x16x32_bf16 v[10:13], v[152:155], v[238:241], v[10:13]
	v_mfma_f32_16x16x32_bf16 v[62:65], v[148:151], v[194:197], v[62:65]
	v_mfma_f32_16x16x32_bf16 v[58:61], v[170:173], v[194:197], v[58:61]
	v_mfma_f32_16x16x32_bf16 v[46:49], v[148:151], v[206:209], v[46:49]
	v_mfma_f32_16x16x32_bf16 v[42:45], v[170:173], v[206:209], v[42:45]
	v_mfma_f32_16x16x32_bf16 v[30:33], v[148:151], v[214:217], v[30:33]
	v_mfma_f32_16x16x32_bf16 v[26:29], v[170:173], v[214:217], v[26:29]
	v_mfma_f32_16x16x32_bf16 v[14:17], v[148:151], v[242:245], v[14:17]
	v_mfma_f32_16x16x32_bf16 v[10:13], v[170:173], v[242:245], v[10:13]
	v_mfma_f32_16x16x32_bf16 v[54:57], v[174:177], v[190:193], v[54:57]
	v_mfma_f32_16x16x32_bf16 v[50:53], v[182:185], v[190:193], v[50:53]
	v_mfma_f32_16x16x32_bf16 v[38:41], v[174:177], v[198:201], v[38:41]
	v_mfma_f32_16x16x32_bf16 v[34:37], v[182:185], v[198:201], v[34:37]
	v_mfma_f32_16x16x32_bf16 v[22:25], v[174:177], v[210:213], v[22:25]
	v_mfma_f32_16x16x32_bf16 v[18:21], v[182:185], v[210:213], v[18:21]
	v_mfma_f32_16x16x32_bf16 v[6:9], v[174:177], v[238:241], v[6:9]
	v_mfma_f32_16x16x32_bf16 v[2:5], v[182:185], v[238:241], v[2:5]
	v_mfma_f32_16x16x32_bf16 v[54:57], v[178:181], v[194:197], v[54:57]
	v_mfma_f32_16x16x32_bf16 v[50:53], v[186:189], v[194:197], v[50:53]
	v_mfma_f32_16x16x32_bf16 v[38:41], v[178:181], v[206:209], v[38:41]
	v_mfma_f32_16x16x32_bf16 v[34:37], v[186:189], v[206:209], v[34:37]
	v_mfma_f32_16x16x32_bf16 v[22:25], v[178:181], v[214:217], v[22:25]
	v_mfma_f32_16x16x32_bf16 v[18:21], v[186:189], v[214:217], v[18:21]
	v_mfma_f32_16x16x32_bf16 v[6:9], v[178:181], v[242:245], v[6:9]
	v_mfma_f32_16x16x32_bf16 v[2:5], v[186:189], v[242:245], v[2:5]
	s_barrier
	s_add_i32 s73, s73, 2
	s_add_u32 s71, s71, 0x100
	s_addc_u32 s72, s72, 0
	s_cmp_gt_u32 s73, 41
	s_mov_b64 s[20:21], s[24:25]
	s_cbranch_scc0 .LBB0_900
	s_setprio 0
	s_and_b64 vcc, exec, s[12:13]
	s_cbranch_vccz .LBB0_903
	s_barrier

.LBB0_959:
	s_ashr_i32 s11, s10, 31
	s_lshl_b64 s[12:13], s[10:11], 19
	s_add_u32 s12, s29, s12
	s_addc_u32 s13, s19, s13
	s_and_b64 s[16:17], s[2:3], exec
	s_cselect_b32 s11, s13, s25
	s_cselect_b32 s67, s12, s24
	s_ashr_i32 s7, s6, 31
	s_lshl_b64 s[16:17], s[6:7], 19
	s_add_u32 s16, s30, s16
	s_addc_u32 s17, s31, s17
	s_and_b64 s[26:27], s[2:3], exec
	s_cselect_b32 s7, s17, s21
	s_cselect_b32 s68, s16, s20
	s_add_u32 s69, s20, 0x100
	s_addc_u32 s70, s21, 0
	s_add_u32 s20, s24, 0x40080
	v_mov_b32_e32 v2, 0
	s_addc_u32 s21, s25, 0
	s_mov_b32 s71, -2
	v_mov_b32_e32 v3, v2
	v_mov_b32_e32 v4, v2
	v_mov_b32_e32 v5, v2
	v_mov_b32_e32 v10, v2
	v_mov_b32_e32 v11, v2
	v_mov_b32_e32 v12, v2
	v_mov_b32_e32 v13, v2
	v_mov_b32_e32 v18, v2
	v_mov_b32_e32 v19, v2
	v_mov_b32_e32 v20, v2
	v_mov_b32_e32 v21, v2
	v_mov_b32_e32 v26, v2
	v_mov_b32_e32 v27, v2
	v_mov_b32_e32 v28, v2
	v_mov_b32_e32 v29, v2
	v_mov_b32_e32 v34, v2
	v_mov_b32_e32 v35, v2
	v_mov_b32_e32 v36, v2
	v_mov_b32_e32 v37, v2
	v_mov_b32_e32 v42, v2
	v_mov_b32_e32 v43, v2
	v_mov_b32_e32 v44, v2
	v_mov_b32_e32 v45, v2
	v_mov_b32_e32 v50, v2
	v_mov_b32_e32 v51, v2
	v_mov_b32_e32 v52, v2
	v_mov_b32_e32 v53, v2
	v_mov_b32_e32 v58, v2
	v_mov_b32_e32 v59, v2
	v_mov_b32_e32 v60, v2
	v_mov_b32_e32 v61, v2
	v_mov_b32_e32 v6, v2
	v_mov_b32_e32 v7, v2
	v_mov_b32_e32 v8, v2
	v_mov_b32_e32 v9, v2
	v_mov_b32_e32 v14, v2
	v_mov_b32_e32 v15, v2
	v_mov_b32_e32 v16, v2
	v_mov_b32_e32 v17, v2
	v_mov_b32_e32 v22, v2
	v_mov_b32_e32 v23, v2
	v_mov_b32_e32 v24, v2
	v_mov_b32_e32 v25, v2
	v_mov_b32_e32 v30, v2
	v_mov_b32_e32 v31, v2
	v_mov_b32_e32 v32, v2
	v_mov_b32_e32 v33, v2
	v_mov_b32_e32 v38, v2
	v_mov_b32_e32 v39, v2
	v_mov_b32_e32 v40, v2
	v_mov_b32_e32 v41, v2
	v_mov_b32_e32 v46, v2
	v_mov_b32_e32 v47, v2
	v_mov_b32_e32 v48, v2
	v_mov_b32_e32 v49, v2
	v_mov_b32_e32 v54, v2
	v_mov_b32_e32 v55, v2
	v_mov_b32_e32 v56, v2
	v_mov_b32_e32 v57, v2
	v_mov_b32_e32 v62, v2
	v_mov_b32_e32 v63, v2
	v_mov_b32_e32 v64, v2
	v_mov_b32_e32 v65, v2
	v_mov_b32_e32 v66, v2
	v_mov_b32_e32 v67, v2
	v_mov_b32_e32 v68, v2
	v_mov_b32_e32 v69, v2
	v_mov_b32_e32 v74, v2
	v_mov_b32_e32 v75, v2
	v_mov_b32_e32 v76, v2
	v_mov_b32_e32 v77, v2
	v_mov_b32_e32 v82, v2
	v_mov_b32_e32 v83, v2
	v_mov_b32_e32 v84, v2
	v_mov_b32_e32 v85, v2
	v_mov_b32_e32 v90, v2
	v_mov_b32_e32 v91, v2
	v_mov_b32_e32 v92, v2
	v_mov_b32_e32 v93, v2
	v_mov_b32_e32 v98, v2
	v_mov_b32_e32 v99, v2
	v_mov_b32_e32 v100, v2
	v_mov_b32_e32 v101, v2
	v_mov_b32_e32 v106, v2
	v_mov_b32_e32 v107, v2
	v_mov_b32_e32 v108, v2
	v_mov_b32_e32 v109, v2
	v_mov_b32_e32 v114, v2
	v_mov_b32_e32 v115, v2
	v_mov_b32_e32 v116, v2
	v_mov_b32_e32 v117, v2
	v_mov_b32_e32 v122, v2
	v_mov_b32_e32 v123, v2
	v_mov_b32_e32 v124, v2
	v_mov_b32_e32 v125, v2
	v_mov_b32_e32 v70, v2
	v_mov_b32_e32 v71, v2
	v_mov_b32_e32 v72, v2
	v_mov_b32_e32 v73, v2
	v_mov_b32_e32 v78, v2
	v_mov_b32_e32 v79, v2
	v_mov_b32_e32 v80, v2
	v_mov_b32_e32 v81, v2
	v_mov_b32_e32 v86, v2
	v_mov_b32_e32 v87, v2
	v_mov_b32_e32 v88, v2
	v_mov_b32_e32 v89, v2
	v_mov_b32_e32 v94, v2
	v_mov_b32_e32 v95, v2
	v_mov_b32_e32 v96, v2
	v_mov_b32_e32 v97, v2
	v_mov_b32_e32 v102, v2
	v_mov_b32_e32 v103, v2
	v_mov_b32_e32 v104, v2
	v_mov_b32_e32 v105, v2
	v_mov_b32_e32 v110, v2
	v_mov_b32_e32 v111, v2
	v_mov_b32_e32 v112, v2
	v_mov_b32_e32 v113, v2
	v_mov_b32_e32 v118, v2
	v_mov_b32_e32 v119, v2
	v_mov_b32_e32 v120, v2
	v_mov_b32_e32 v121, v2
	v_mov_b32_e32 v126, v2
	v_mov_b32_e32 v127, v2
	v_mov_b32_e32 v128, v2
	v_mov_b32_e32 v129, v2
	v_readfirstlane_b32 vcc_lo, v169
	s_nop 0
	s_bitcmp1_b32 vcc_lo, 8
	s_cbranch_scc0 .Lprio_skip_gu
	s_setprio 1
.Lprio_skip_gu:
.LBB0_960:
	s_add_u32 s24, s20, 0xfffc0080
	s_addc_u32 s25, s21, -1
	s_add_i32 s72, 0, 0x10000
	s_cmp_eq_u32 s71, 12
	s_cselect_b32 s27, s11, s25
	s_cselect_b32 s26, s67, s24
	v_add_u32_e32 v140, s72, v143
	s_cselect_b32 s25, s7, s70
	s_cselect_b32 s24, s68, s69
	s_add_i32 s74, 0, 0x14000
	ds_read_b128 v[148:151], v140
	ds_read_b128 v[152:155], v140 offset:1024
	ds_read_b128 v[170:173], v140 offset:2048
	ds_read_b128 v[174:177], v140 offset:3072
	v_add_u32_e32 v140, s74, v143
	ds_read_b128 v[178:181], v140
	ds_read_b128 v[182:185], v140 offset:1024
	ds_read_b128 v[186:189], v140 offset:2048
	ds_read_b128 v[190:193], v140 offset:3072
	v_lshl_add_u64 v[140:141], s[20:21], 0, v[138:139]
	s_add_i32 m0, s34, 0xc000
	ds_read_b128 v[194:197], v146
	ds_read_b128 v[198:201], v146 offset:1024
	ds_read_b128 v[206:209], v146 offset:2048
	ds_read_b128 v[210:213], v146 offset:3072
	ds_read_b128 v[214:217], v146 offset:4096
	ds_read_b128 v[238:241], v146 offset:5120
	ds_read_b128 v[242:245], v146 offset:6144
	ds_read_b128 v[246:249], v146 offset:7168
	global_load_lds_dwordx4 v[140:141], off
	v_lshl_add_u64 v[140:141], s[20:21], 0, v[136:137]
	s_add_i32 m0, s34, 0xe000
	s_nop 0
	global_load_lds_dwordx4 v[140:141], off
	s_waitcnt vmcnt(8)
	s_waitcnt lgkmcnt(0)
	s_barrier
	s_waitcnt lgkmcnt(0)
	v_mfma_f32_16x16x32_bf16 v[126:129], v[148:151], v[194:197], v[126:129]
	v_mfma_f32_16x16x32_bf16 v[118:121], v[170:173], v[194:197], v[118:121]
	v_mfma_f32_16x16x32_bf16 v[110:113], v[148:151], v[206:209], v[110:113]
	v_mfma_f32_16x16x32_bf16 v[102:105], v[170:173], v[206:209], v[102:105]
	v_mfma_f32_16x16x32_bf16 v[94:97], v[148:151], v[214:217], v[94:97]
	v_mfma_f32_16x16x32_bf16 v[86:89], v[170:173], v[214:217], v[86:89]
	v_mfma_f32_16x16x32_bf16 v[78:81], v[148:151], v[242:245], v[78:81]
	v_mfma_f32_16x16x32_bf16 v[70:73], v[170:173], v[242:245], v[70:73]
	v_mfma_f32_16x16x32_bf16 v[126:129], v[152:155], v[198:201], v[126:129]
	v_mfma_f32_16x16x32_bf16 v[118:121], v[174:177], v[198:201], v[118:121]
	v_mfma_f32_16x16x32_bf16 v[110:113], v[152:155], v[210:213], v[110:113]
	v_mfma_f32_16x16x32_bf16 v[102:105], v[174:177], v[210:213], v[102:105]
	v_mfma_f32_16x16x32_bf16 v[94:97], v[152:155], v[238:241], v[94:97]
	v_mfma_f32_16x16x32_bf16 v[86:89], v[174:177], v[238:241], v[86:89]
	v_mfma_f32_16x16x32_bf16 v[78:81], v[152:155], v[246:249], v[78:81]
	v_mfma_f32_16x16x32_bf16 v[70:73], v[174:177], v[246:249], v[70:73]
	v_mfma_f32_16x16x32_bf16 v[122:125], v[178:181], v[194:197], v[122:125]
	v_mfma_f32_16x16x32_bf16 v[114:117], v[186:189], v[194:197], v[114:117]
	v_mfma_f32_16x16x32_bf16 v[106:109], v[178:181], v[206:209], v[106:109]
	v_mfma_f32_16x16x32_bf16 v[98:101], v[186:189], v[206:209], v[98:101]
	v_mfma_f32_16x16x32_bf16 v[90:93], v[178:181], v[214:217], v[90:93]
	v_mfma_f32_16x16x32_bf16 v[82:85], v[186:189], v[214:217], v[82:85]
	v_mfma_f32_16x16x32_bf16 v[74:77], v[178:181], v[242:245], v[74:77]
	v_mfma_f32_16x16x32_bf16 v[66:69], v[186:189], v[242:245], v[66:69]
	v_mfma_f32_16x16x32_bf16 v[122:125], v[182:185], v[198:201], v[122:125]
	v_mfma_f32_16x16x32_bf16 v[114:117], v[190:193], v[198:201], v[114:117]
	v_mfma_f32_16x16x32_bf16 v[106:109], v[182:185], v[210:213], v[106:109]
	v_mfma_f32_16x16x32_bf16 v[98:101], v[190:193], v[210:213], v[98:101]
	v_mfma_f32_16x16x32_bf16 v[90:93], v[182:185], v[238:241], v[90:93]
	v_mfma_f32_16x16x32_bf16 v[82:85], v[190:193], v[238:241], v[82:85]
	v_mfma_f32_16x16x32_bf16 v[74:77], v[182:185], v[246:249], v[74:77]
	v_mfma_f32_16x16x32_bf16 v[66:69], v[190:193], v[246:249], v[66:69]
	s_barrier
	s_add_i32 s72, s72, s18
	v_lshl_add_u64 v[140:141], s[24:25], 0, v[0:1]
	s_mov_b32 m0, s72
	ds_read_b128 v[194:197], v146 offset:16384
	ds_read_b128 v[198:201], v146 offset:17408
	ds_read_b128 v[206:209], v146 offset:18432
	ds_read_b128 v[210:213], v146 offset:19456
	ds_read_b128 v[214:217], v146 offset:20480
	ds_read_b128 v[238:241], v146 offset:21504
	ds_read_b128 v[242:245], v146 offset:22528
	ds_read_b128 v[246:249], v146 offset:23552
	global_load_lds_dwordx4 v[140:141], off
	s_add_i32 m0, s72, 0x2000
	s_add_u32 s72, s24, 0x40000
	v_lshl_add_u64 v[156:157], s[24:25], 0, v[130:131]
	s_addc_u32 s73, s25, 0
	s_add_i32 s74, s74, s18
	global_load_lds_dwordx4 v[156:157], off
	v_lshl_add_u64 v[202:203], s[72:73], 0, v[0:1]
	s_mov_b32 m0, s74
	v_lshl_add_u64 v[250:251], s[26:27], 0, v[132:133]
	global_load_lds_dwordx4 v[202:203], off
	v_lshl_add_u64 v[202:203], s[72:73], 0, v[130:131]
	s_add_i32 m0, s74, 0x2000
	s_nop 0
	global_load_lds_dwordx4 v[202:203], off
	v_lshl_add_u64 v[202:203], s[26:27], 0, v[134:135]
	s_mov_b32 m0, s34
	s_nop 0
	global_load_lds_dwordx4 v[202:203], off
	s_mov_b32 m0, s35
	s_nop 0
	global_load_lds_dwordx4 v[250:251], off
	s_waitcnt vmcnt(8)
	s_waitcnt lgkmcnt(0)
	s_barrier
	s_waitcnt lgkmcnt(0)
	v_mfma_f32_16x16x32_bf16 v[62:65], v[148:151], v[194:197], v[62:65]
	v_mfma_f32_16x16x32_bf16 v[54:57], v[170:173], v[194:197], v[54:57]
	v_mfma_f32_16x16x32_bf16 v[46:49], v[148:151], v[206:209], v[46:49]
	v_mfma_f32_16x16x32_bf16 v[38:41], v[170:173], v[206:209], v[38:41]
	v_mfma_f32_16x16x32_bf16 v[30:33], v[148:151], v[214:217], v[30:33]
	v_mfma_f32_16x16x32_bf16 v[22:25], v[170:173], v[214:217], v[22:25]
	v_mfma_f32_16x16x32_bf16 v[14:17], v[148:151], v[242:245], v[14:17]
	v_mfma_f32_16x16x32_bf16 v[6:9], v[170:173], v[242:245], v[6:9]
	v_mfma_f32_16x16x32_bf16 v[62:65], v[152:155], v[198:201], v[62:65]
	v_mfma_f32_16x16x32_bf16 v[54:57], v[174:177], v[198:201], v[54:57]
	v_mfma_f32_16x16x32_bf16 v[46:49], v[152:155], v[210:213], v[46:49]
	v_mfma_f32_16x16x32_bf16 v[38:41], v[174:177], v[210:213], v[38:41]
	v_mfma_f32_16x16x32_bf16 v[30:33], v[152:155], v[238:241], v[30:33]
	v_mfma_f32_16x16x32_bf16 v[22:25], v[174:177], v[238:241], v[22:25]
	v_mfma_f32_16x16x32_bf16 v[14:17], v[152:155], v[246:249], v[14:17]
	v_mfma_f32_16x16x32_bf16 v[6:9], v[174:177], v[246:249], v[6:9]
	v_mfma_f32_16x16x32_bf16 v[58:61], v[178:181], v[194:197], v[58:61]
	v_mfma_f32_16x16x32_bf16 v[50:53], v[186:189], v[194:197], v[50:53]
	v_mfma_f32_16x16x32_bf16 v[42:45], v[178:181], v[206:209], v[42:45]
	v_mfma_f32_16x16x32_bf16 v[34:37], v[186:189], v[206:209], v[34:37]
	v_mfma_f32_16x16x32_bf16 v[26:29], v[178:181], v[214:217], v[26:29]
	v_mfma_f32_16x16x32_bf16 v[18:21], v[186:189], v[214:217], v[18:21]
	v_mfma_f32_16x16x32_bf16 v[10:13], v[178:181], v[242:245], v[10:13]
	v_mfma_f32_16x16x32_bf16 v[2:5], v[186:189], v[242:245], v[2:5]
	v_mfma_f32_16x16x32_bf16 v[58:61], v[182:185], v[198:201], v[58:61]
	v_mfma_f32_16x16x32_bf16 v[50:53], v[190:193], v[198:201], v[50:53]
	v_mfma_f32_16x16x32_bf16 v[42:45], v[182:185], v[210:213], v[42:45]
	v_mfma_f32_16x16x32_bf16 v[34:37], v[190:193], v[210:213], v[34:37]
	v_mfma_f32_16x16x32_bf16 v[26:29], v[182:185], v[238:241], v[26:29]
	v_mfma_f32_16x16x32_bf16 v[18:21], v[190:193], v[238:241], v[18:21]
	v_mfma_f32_16x16x32_bf16 v[10:13], v[182:185], v[246:249], v[10:13]
	v_mfma_f32_16x16x32_bf16 v[2:5], v[190:193], v[246:249], v[2:5]
	s_barrier
	s_add_i32 s72, 0, 0x18000
	v_add_u32_e32 v147, s72, v143
	s_add_i32 s73, 0, 0x1c000
	ds_read_b128 v[148:151], v147
	ds_read_b128 v[152:155], v147 offset:1024
	ds_read_b128 v[170:173], v147 offset:2048
	ds_read_b128 v[174:177], v147 offset:3072
	v_add_u32_e32 v147, s73, v143
	ds_read_b128 v[178:181], v147
	ds_read_b128 v[182:185], v147 offset:1024
	ds_read_b128 v[186:189], v147 offset:2048
	ds_read_b128 v[190:193], v147 offset:3072
	s_add_u32 s26, s26, 0x40000
	s_addc_u32 s27, s27, 0
	s_mov_b32 m0, s38
	v_lshl_add_u64 v[220:221], s[26:27], 0, v[134:135]
	ds_read_b128 v[194:197], v146 offset:32768
	ds_read_b128 v[198:201], v146 offset:33792
	ds_read_b128 v[206:209], v146 offset:34816
	ds_read_b128 v[210:213], v146 offset:35840
	ds_read_b128 v[214:217], v146 offset:36864
	ds_read_b128 v[238:241], v146 offset:37888
	ds_read_b128 v[242:245], v146 offset:38912
	ds_read_b128 v[246:249], v146 offset:39936
	global_load_lds_dwordx4 v[220:221], off
	v_lshl_add_u64 v[220:221], s[26:27], 0, v[132:133]
	s_mov_b32 m0, s39
	s_nop 0
	global_load_lds_dwordx4 v[220:221], off
	s_waitcnt vmcnt(8)
	s_waitcnt lgkmcnt(0)
	s_barrier
	s_waitcnt lgkmcnt(0)
	v_mfma_f32_16x16x32_bf16 v[126:129], v[148:151], v[194:197], v[126:129]
	v_mfma_f32_16x16x32_bf16 v[118:121], v[170:173], v[194:197], v[118:121]
	v_mfma_f32_16x16x32_bf16 v[110:113], v[148:151], v[206:209], v[110:113]
	v_mfma_f32_16x16x32_bf16 v[102:105], v[170:173], v[206:209], v[102:105]
	v_mfma_f32_16x16x32_bf16 v[94:97], v[148:151], v[214:217], v[94:97]
	v_mfma_f32_16x16x32_bf16 v[86:89], v[170:173], v[214:217], v[86:89]
	v_mfma_f32_16x16x32_bf16 v[78:81], v[148:151], v[242:245], v[78:81]
	v_mfma_f32_16x16x32_bf16 v[70:73], v[170:173], v[242:245], v[70:73]
	v_mfma_f32_16x16x32_bf16 v[126:129], v[152:155], v[198:201], v[126:129]
	v_mfma_f32_16x16x32_bf16 v[118:121], v[174:177], v[198:201], v[118:121]
	v_mfma_f32_16x16x32_bf16 v[110:113], v[152:155], v[210:213], v[110:113]
	v_mfma_f32_16x16x32_bf16 v[102:105], v[174:177], v[210:213], v[102:105]
	v_mfma_f32_16x16x32_bf16 v[94:97], v[152:155], v[238:241], v[94:97]
	v_mfma_f32_16x16x32_bf16 v[86:89], v[174:177], v[238:241], v[86:89]
	v_mfma_f32_16x16x32_bf16 v[78:81], v[152:155], v[246:249], v[78:81]
	v_mfma_f32_16x16x32_bf16 v[70:73], v[174:177], v[246:249], v[70:73]
	v_mfma_f32_16x16x32_bf16 v[122:125], v[178:181], v[194:197], v[122:125]
	v_mfma_f32_16x16x32_bf16 v[114:117], v[186:189], v[194:197], v[114:117]
	v_mfma_f32_16x16x32_bf16 v[106:109], v[178:181], v[206:209], v[106:109]
	v_mfma_f32_16x16x32_bf16 v[98:101], v[186:189], v[206:209], v[98:101]
	v_mfma_f32_16x16x32_bf16 v[90:93], v[178:181], v[214:217], v[90:93]
	v_mfma_f32_16x16x32_bf16 v[82:85], v[186:189], v[214:217], v[82:85]
	v_mfma_f32_16x16x32_bf16 v[74:77], v[178:181], v[242:245], v[74:77]
	v_mfma_f32_16x16x32_bf16 v[66:69], v[186:189], v[242:245], v[66:69]
	v_mfma_f32_16x16x32_bf16 v[122:125], v[182:185], v[198:201], v[122:125]
	v_mfma_f32_16x16x32_bf16 v[114:117], v[190:193], v[198:201], v[114:117]
	v_mfma_f32_16x16x32_bf16 v[106:109], v[182:185], v[210:213], v[106:109]
	v_mfma_f32_16x16x32_bf16 v[98:101], v[190:193], v[210:213], v[98:101]
	v_mfma_f32_16x16x32_bf16 v[90:93], v[182:185], v[238:241], v[90:93]
	v_mfma_f32_16x16x32_bf16 v[82:85], v[190:193], v[238:241], v[82:85]
	v_mfma_f32_16x16x32_bf16 v[74:77], v[182:185], v[246:249], v[74:77]
	v_mfma_f32_16x16x32_bf16 v[66:69], v[190:193], v[246:249], v[66:69]
	s_barrier
	s_add_i32 s26, s72, s18
	v_lshl_add_u64 v[140:141], v[140:141], 0, s[22:23]
	s_mov_b32 m0, s26
	ds_read_b128 v[194:197], v146 offset:49152
	ds_read_b128 v[198:201], v146 offset:50176
	ds_read_b128 v[206:209], v146 offset:51200
	ds_read_b128 v[210:213], v146 offset:52224
	ds_read_b128 v[214:217], v146 offset:53248
	ds_read_b128 v[238:241], v146 offset:54272
	ds_read_b128 v[242:245], v146 offset:55296
	ds_read_b128 v[246:249], v146 offset:56320
	global_load_lds_dwordx4 v[140:141], off
	s_add_i32 m0, s26, 0x2000
	s_add_u32 s24, s24, 0x40080
	v_lshl_add_u64 v[140:141], v[156:157], 0, s[22:23]
	s_addc_u32 s25, s25, 0
	s_add_i32 s26, s73, s18
	global_load_lds_dwordx4 v[140:141], off
	v_lshl_add_u64 v[140:141], s[24:25], 0, v[0:1]
	s_mov_b32 m0, s26
	s_nop 0
	global_load_lds_dwordx4 v[140:141], off
	v_lshl_add_u64 v[140:141], s[24:25], 0, v[130:131]
	s_add_i32 m0, s26, 0x2000
	s_nop 0
	global_load_lds_dwordx4 v[140:141], off
	v_lshl_add_u64 v[140:141], v[202:203], 0, s[22:23]
	s_mov_b32 m0, s57
	s_nop 0
	global_load_lds_dwordx4 v[140:141], off
	v_lshl_add_u64 v[140:141], v[250:251], 0, s[22:23]
	s_mov_b32 m0, s61
	s_nop 0
	global_load_lds_dwordx4 v[140:141], off
	s_waitcnt vmcnt(8)
	s_waitcnt lgkmcnt(0)
	s_barrier
	s_waitcnt lgkmcnt(0)
	v_mfma_f32_16x16x32_bf16 v[62:65], v[148:151], v[194:197], v[62:65]
	v_mfma_f32_16x16x32_bf16 v[54:57], v[170:173], v[194:197], v[54:57]
	v_mfma_f32_16x16x32_bf16 v[46:49], v[148:151], v[206:209], v[46:49]
	v_mfma_f32_16x16x32_bf16 v[38:41], v[170:173], v[206:209], v[38:41]
	v_mfma_f32_16x16x32_bf16 v[30:33], v[148:151], v[214:217], v[30:33]
	v_mfma_f32_16x16x32_bf16 v[22:25], v[170:173], v[214:217], v[22:25]
	v_mfma_f32_16x16x32_bf16 v[14:17], v[148:151], v[242:245], v[14:17]
	v_mfma_f32_16x16x32_bf16 v[6:9], v[170:173], v[242:245], v[6:9]
	v_mfma_f32_16x16x32_bf16 v[62:65], v[152:155], v[198:201], v[62:65]
	v_mfma_f32_16x16x32_bf16 v[54:57], v[174:177], v[198:201], v[54:57]
	v_mfma_f32_16x16x32_bf16 v[46:49], v[152:155], v[210:213], v[46:49]
	v_mfma_f32_16x16x32_bf16 v[38:41], v[174:177], v[210:213], v[38:41]
	v_mfma_f32_16x16x32_bf16 v[30:33], v[152:155], v[238:241], v[30:33]
	v_mfma_f32_16x16x32_bf16 v[22:25], v[174:177], v[238:241], v[22:25]
	v_mfma_f32_16x16x32_bf16 v[14:17], v[152:155], v[246:249], v[14:17]
	v_mfma_f32_16x16x32_bf16 v[6:9], v[174:177], v[246:249], v[6:9]
	v_mfma_f32_16x16x32_bf16 v[58:61], v[178:181], v[194:197], v[58:61]
	v_mfma_f32_16x16x32_bf16 v[50:53], v[186:189], v[194:197], v[50:53]
	v_mfma_f32_16x16x32_bf16 v[42:45], v[178:181], v[206:209], v[42:45]
	v_mfma_f32_16x16x32_bf16 v[34:37], v[186:189], v[206:209], v[34:37]
	v_mfma_f32_16x16x32_bf16 v[26:29], v[178:181], v[214:217], v[26:29]
	v_mfma_f32_16x16x32_bf16 v[18:21], v[186:189], v[214:217], v[18:21]
	v_mfma_f32_16x16x32_bf16 v[10:13], v[178:181], v[242:245], v[10:13]
	v_mfma_f32_16x16x32_bf16 v[2:5], v[186:189], v[242:245], v[2:5]
	v_mfma_f32_16x16x32_bf16 v[58:61], v[182:185], v[198:201], v[58:61]
	v_mfma_f32_16x16x32_bf16 v[50:53], v[190:193], v[198:201], v[50:53]
	v_mfma_f32_16x16x32_bf16 v[42:45], v[182:185], v[210:213], v[42:45]
	v_mfma_f32_16x16x32_bf16 v[34:37], v[190:193], v[210:213], v[34:37]
	v_mfma_f32_16x16x32_bf16 v[26:29], v[182:185], v[238:241], v[26:29]
	v_mfma_f32_16x16x32_bf16 v[18:21], v[190:193], v[238:241], v[18:21]
	v_mfma_f32_16x16x32_bf16 v[10:13], v[182:185], v[246:249], v[10:13]
	v_mfma_f32_16x16x32_bf16 v[2:5], v[190:193], v[246:249], v[2:5]
	s_barrier
	s_add_i32 s71, s71, 2
	s_add_u32 s69, s69, 0x100
	s_addc_u32 s70, s70, 0
	s_add_u32 s20, s20, 0x100
	s_addc_u32 s21, s21, 0
	s_cmp_gt_u32 s71, 13
	s_cbranch_scc0 .LBB0_960
	s_setprio 0
	s_and_b64 vcc, exec, s[4:5]
	s_cbranch_vccz .LBB0_963
	s_barrier

.LBB0_992:
	s_ashr_i32 s19, s18, 31
	s_lshl_b64 s[20:21], s[18:19], 19
	v_readlane_b32 s30, v254, 21
	v_readlane_b32 s31, v254, 22
	s_add_u32 s20, s30, s20
	s_addc_u32 s21, s31, s21
	s_and_b64 s[30:31], s[4:5], exec
	s_cselect_b32 s19, s21, s29
	s_cselect_b32 s25, s20, s28
	s_ashr_i32 s17, s16, 31
	s_lshl_b64 s[30:31], s[16:17], 19
	s_add_u32 s38, s0, s30
	s_addc_u32 s39, s1, s31
	s_and_b64 s[30:31], s[4:5], exec
	s_cselect_b32 s17, s39, s27
	s_cselect_b32 s71, s38, s26
	s_add_u32 s73, s26, 0x100
	s_addc_u32 s74, s27, 0
	s_add_u32 s26, s28, 0x40080
	v_mov_b32_e32 v2, 0
	s_addc_u32 s27, s29, 0
	s_mov_b32 s75, -2
	s_waitcnt lgkmcnt(0)
	v_mov_b32_e32 v3, v2
	v_mov_b32_e32 v4, v2
	v_mov_b32_e32 v5, v2
	v_mov_b32_e32 v6, v2
	v_mov_b32_e32 v7, v2
	v_mov_b32_e32 v8, v2
	v_mov_b32_e32 v9, v2
	v_mov_b32_e32 v18, v2
	v_mov_b32_e32 v19, v2
	v_mov_b32_e32 v20, v2
	v_mov_b32_e32 v21, v2
	v_mov_b32_e32 v22, v2
	v_mov_b32_e32 v23, v2
	v_mov_b32_e32 v24, v2
	v_mov_b32_e32 v25, v2
	v_mov_b32_e32 v34, v2
	v_mov_b32_e32 v35, v2
	v_mov_b32_e32 v36, v2
	v_mov_b32_e32 v37, v2
	v_mov_b32_e32 v38, v2
	v_mov_b32_e32 v39, v2
	v_mov_b32_e32 v40, v2
	v_mov_b32_e32 v41, v2
	v_mov_b32_e32 v50, v2
	v_mov_b32_e32 v51, v2
	v_mov_b32_e32 v52, v2
	v_mov_b32_e32 v53, v2
	v_mov_b32_e32 v54, v2
	v_mov_b32_e32 v55, v2
	v_mov_b32_e32 v56, v2
	v_mov_b32_e32 v57, v2
	v_mov_b32_e32 v10, v2
	v_mov_b32_e32 v11, v2
	v_mov_b32_e32 v12, v2
	v_mov_b32_e32 v13, v2
	v_mov_b32_e32 v14, v2
	v_mov_b32_e32 v15, v2
	v_mov_b32_e32 v16, v2
	v_mov_b32_e32 v17, v2
	v_mov_b32_e32 v26, v2
	v_mov_b32_e32 v27, v2
	v_mov_b32_e32 v28, v2
	v_mov_b32_e32 v29, v2
	v_mov_b32_e32 v30, v2
	v_mov_b32_e32 v31, v2
	v_mov_b32_e32 v32, v2
	v_mov_b32_e32 v33, v2
	v_mov_b32_e32 v42, v2
	v_mov_b32_e32 v43, v2
	v_mov_b32_e32 v44, v2
	v_mov_b32_e32 v45, v2
	v_mov_b32_e32 v46, v2
	v_mov_b32_e32 v47, v2
	v_mov_b32_e32 v48, v2
	v_mov_b32_e32 v49, v2
	v_mov_b32_e32 v58, v2
	v_mov_b32_e32 v59, v2
	v_mov_b32_e32 v60, v2
	v_mov_b32_e32 v61, v2
	v_mov_b32_e32 v62, v2
	v_mov_b32_e32 v63, v2
	v_mov_b32_e32 v64, v2
	v_mov_b32_e32 v65, v2
	v_mov_b32_e32 v66, v2
	v_mov_b32_e32 v67, v2
	v_mov_b32_e32 v68, v2
	v_mov_b32_e32 v69, v2
	v_mov_b32_e32 v70, v2
	v_mov_b32_e32 v71, v2
	v_mov_b32_e32 v72, v2
	v_mov_b32_e32 v73, v2
	v_mov_b32_e32 v82, v2
	v_mov_b32_e32 v83, v2
	v_mov_b32_e32 v84, v2
	v_mov_b32_e32 v85, v2
	v_mov_b32_e32 v86, v2
	v_mov_b32_e32 v87, v2
	v_mov_b32_e32 v88, v2
	v_mov_b32_e32 v89, v2
	v_mov_b32_e32 v98, v2
	v_mov_b32_e32 v99, v2
	v_mov_b32_e32 v100, v2
	v_mov_b32_e32 v101, v2
	v_mov_b32_e32 v102, v2
	v_mov_b32_e32 v103, v2
	v_mov_b32_e32 v104, v2
	v_mov_b32_e32 v105, v2
	v_mov_b32_e32 v114, v2
	v_mov_b32_e32 v115, v2
	v_mov_b32_e32 v116, v2
	v_mov_b32_e32 v117, v2
	v_mov_b32_e32 v118, v2
	v_mov_b32_e32 v119, v2
	v_mov_b32_e32 v120, v2
	v_mov_b32_e32 v121, v2
	v_mov_b32_e32 v74, v2
	v_mov_b32_e32 v75, v2
	v_mov_b32_e32 v76, v2
	v_mov_b32_e32 v77, v2
	v_mov_b32_e32 v78, v2
	v_mov_b32_e32 v79, v2
	v_mov_b32_e32 v80, v2
	v_mov_b32_e32 v81, v2
	v_mov_b32_e32 v90, v2
	v_mov_b32_e32 v91, v2
	v_mov_b32_e32 v92, v2
	v_mov_b32_e32 v93, v2
	v_mov_b32_e32 v94, v2
	v_mov_b32_e32 v95, v2
	v_mov_b32_e32 v96, v2
	v_mov_b32_e32 v97, v2
	v_mov_b32_e32 v106, v2
	v_mov_b32_e32 v107, v2
	v_mov_b32_e32 v108, v2
	v_mov_b32_e32 v109, v2
	v_mov_b32_e32 v110, v2
	v_mov_b32_e32 v111, v2
	v_mov_b32_e32 v112, v2
	v_mov_b32_e32 v113, v2
	v_mov_b32_e32 v122, v2
	v_mov_b32_e32 v123, v2
	v_mov_b32_e32 v124, v2
	v_mov_b32_e32 v125, v2
	v_mov_b32_e32 v126, v2
	v_mov_b32_e32 v127, v2
	v_mov_b32_e32 v128, v2
	v_mov_b32_e32 v129, v2
	v_readfirstlane_b32 vcc_lo, v169
	s_nop 0
	s_bitcmp1_b32 vcc_lo, 8
	s_cbranch_scc0 .Lprio_skip_op
	s_setprio 1
.Lprio_skip_op:
.LBB0_993:
	s_add_u32 s28, s26, 0xfffc0080
	s_addc_u32 s29, s27, -1
	s_add_i32 s76, 0, 0x10000
	s_cmp_eq_u32 s75, 12
	s_cselect_b32 s31, s19, s29
	s_cselect_b32 s30, s25, s28
	v_add_u32_e32 v156, s76, v145
	s_cselect_b32 s29, s17, s74
	s_cselect_b32 s28, s71, s73
	s_add_i32 s78, 0, 0x14000
	ds_read_b128 v[140:143], v156
	ds_read_b128 v[148:151], v156 offset:1024
	ds_read_b128 v[152:155], v156 offset:2048
	ds_read_b128 v[170:173], v156 offset:3072
	v_add_u32_e32 v156, s78, v145
	ds_read_b128 v[174:177], v156
	ds_read_b128 v[178:181], v156 offset:1024
	ds_read_b128 v[182:185], v156 offset:2048
	ds_read_b128 v[186:189], v156 offset:3072
	v_lshl_add_u64 v[156:157], s[26:27], 0, v[138:139]
	s_add_i32 m0, s35, 0xc000
	ds_read_b128 v[190:193], v147
	ds_read_b128 v[194:197], v147 offset:1024
	ds_read_b128 v[198:201], v147 offset:2048
	ds_read_b128 v[206:209], v147 offset:3072
	ds_read_b128 v[210:213], v147 offset:4096
	ds_read_b128 v[214:217], v147 offset:5120
	ds_read_b128 v[238:241], v147 offset:6144
	ds_read_b128 v[242:245], v147 offset:7168
	global_load_lds_dwordx4 v[156:157], off
	v_lshl_add_u64 v[156:157], s[26:27], 0, v[136:137]
	s_add_i32 m0, s35, 0xe000
	s_nop 0
	global_load_lds_dwordx4 v[156:157], off
	s_waitcnt vmcnt(8)
	s_waitcnt lgkmcnt(0)
	s_barrier
	s_waitcnt lgkmcnt(0)
	v_mfma_f32_16x16x32_bf16 v[126:129], v[140:143], v[190:193], v[126:129]
	v_mfma_f32_16x16x32_bf16 v[122:125], v[152:155], v[190:193], v[122:125]
	v_mfma_f32_16x16x32_bf16 v[110:113], v[140:143], v[198:201], v[110:113]
	v_mfma_f32_16x16x32_bf16 v[106:109], v[152:155], v[198:201], v[106:109]
	v_mfma_f32_16x16x32_bf16 v[94:97], v[140:143], v[210:213], v[94:97]
	v_mfma_f32_16x16x32_bf16 v[90:93], v[152:155], v[210:213], v[90:93]
	v_mfma_f32_16x16x32_bf16 v[78:81], v[140:143], v[238:241], v[78:81]
	v_mfma_f32_16x16x32_bf16 v[74:77], v[152:155], v[238:241], v[74:77]
	v_mfma_f32_16x16x32_bf16 v[126:129], v[148:151], v[194:197], v[126:129]
	v_mfma_f32_16x16x32_bf16 v[122:125], v[170:173], v[194:197], v[122:125]
	v_mfma_f32_16x16x32_bf16 v[110:113], v[148:151], v[206:209], v[110:113]
	v_mfma_f32_16x16x32_bf16 v[106:109], v[170:173], v[206:209], v[106:109]
	v_mfma_f32_16x16x32_bf16 v[94:97], v[148:151], v[214:217], v[94:97]
	v_mfma_f32_16x16x32_bf16 v[90:93], v[170:173], v[214:217], v[90:93]
	v_mfma_f32_16x16x32_bf16 v[78:81], v[148:151], v[242:245], v[78:81]
	v_mfma_f32_16x16x32_bf16 v[74:77], v[170:173], v[242:245], v[74:77]
	v_mfma_f32_16x16x32_bf16 v[118:121], v[174:177], v[190:193], v[118:121]
	v_mfma_f32_16x16x32_bf16 v[114:117], v[182:185], v[190:193], v[114:117]
	v_mfma_f32_16x16x32_bf16 v[102:105], v[174:177], v[198:201], v[102:105]
	v_mfma_f32_16x16x32_bf16 v[98:101], v[182:185], v[198:201], v[98:101]
	v_mfma_f32_16x16x32_bf16 v[86:89], v[174:177], v[210:213], v[86:89]
	v_mfma_f32_16x16x32_bf16 v[82:85], v[182:185], v[210:213], v[82:85]
	v_mfma_f32_16x16x32_bf16 v[70:73], v[174:177], v[238:241], v[70:73]
	v_mfma_f32_16x16x32_bf16 v[66:69], v[182:185], v[238:241], v[66:69]
	v_mfma_f32_16x16x32_bf16 v[118:121], v[178:181], v[194:197], v[118:121]
	v_mfma_f32_16x16x32_bf16 v[114:117], v[186:189], v[194:197], v[114:117]
	v_mfma_f32_16x16x32_bf16 v[102:105], v[178:181], v[206:209], v[102:105]
	v_mfma_f32_16x16x32_bf16 v[98:101], v[186:189], v[206:209], v[98:101]
	v_mfma_f32_16x16x32_bf16 v[86:89], v[178:181], v[214:217], v[86:89]
	v_mfma_f32_16x16x32_bf16 v[82:85], v[186:189], v[214:217], v[82:85]
	v_mfma_f32_16x16x32_bf16 v[70:73], v[178:181], v[242:245], v[70:73]
	v_mfma_f32_16x16x32_bf16 v[66:69], v[186:189], v[242:245], v[66:69]
	s_barrier
	s_add_i32 s76, s76, s34
	v_lshl_add_u64 v[156:157], s[28:29], 0, v[0:1]
	s_mov_b32 m0, s76
	ds_read_b128 v[190:193], v147 offset:16384
	ds_read_b128 v[194:197], v147 offset:17408
	ds_read_b128 v[198:201], v147 offset:18432
	ds_read_b128 v[206:209], v147 offset:19456
	ds_read_b128 v[210:213], v147 offset:20480
	ds_read_b128 v[214:217], v147 offset:21504
	ds_read_b128 v[238:241], v147 offset:22528
	ds_read_b128 v[242:245], v147 offset:23552
	global_load_lds_dwordx4 v[156:157], off
	s_add_i32 m0, s76, 0x2000
	s_add_u32 s76, s28, 0x40000
	v_lshl_add_u64 v[202:203], s[28:29], 0, v[134:135]
	s_addc_u32 s77, s29, 0
	s_add_i32 s78, s78, s34
	global_load_lds_dwordx4 v[202:203], off
	v_lshl_add_u64 v[220:221], s[76:77], 0, v[0:1]
	s_mov_b32 m0, s78
	v_lshl_add_u64 v[226:227], s[30:31], 0, v[132:133]
	global_load_lds_dwordx4 v[220:221], off
	v_lshl_add_u64 v[220:221], s[76:77], 0, v[134:135]
	s_add_i32 m0, s78, 0x2000
	s_nop 0
	global_load_lds_dwordx4 v[220:221], off
	v_lshl_add_u64 v[220:221], s[30:31], 0, v[130:131]
	s_mov_b32 m0, s35
	s_nop 0
	global_load_lds_dwordx4 v[220:221], off
	s_mov_b32 m0, s57
	s_nop 0
	global_load_lds_dwordx4 v[226:227], off
	s_waitcnt vmcnt(8)
	s_waitcnt lgkmcnt(0)
	s_barrier
	s_waitcnt lgkmcnt(0)
	v_mfma_f32_16x16x32_bf16 v[62:65], v[140:143], v[190:193], v[62:65]
	v_mfma_f32_16x16x32_bf16 v[58:61], v[152:155], v[190:193], v[58:61]
	v_mfma_f32_16x16x32_bf16 v[46:49], v[140:143], v[198:201], v[46:49]
	v_mfma_f32_16x16x32_bf16 v[42:45], v[152:155], v[198:201], v[42:45]
	v_mfma_f32_16x16x32_bf16 v[30:33], v[140:143], v[210:213], v[30:33]
	v_mfma_f32_16x16x32_bf16 v[26:29], v[152:155], v[210:213], v[26:29]
	v_mfma_f32_16x16x32_bf16 v[14:17], v[140:143], v[238:241], v[14:17]
	v_mfma_f32_16x16x32_bf16 v[10:13], v[152:155], v[238:241], v[10:13]
	v_mfma_f32_16x16x32_bf16 v[62:65], v[148:151], v[194:197], v[62:65]
	v_mfma_f32_16x16x32_bf16 v[58:61], v[170:173], v[194:197], v[58:61]
	v_mfma_f32_16x16x32_bf16 v[46:49], v[148:151], v[206:209], v[46:49]
	v_mfma_f32_16x16x32_bf16 v[42:45], v[170:173], v[206:209], v[42:45]
	v_mfma_f32_16x16x32_bf16 v[30:33], v[148:151], v[214:217], v[30:33]
	v_mfma_f32_16x16x32_bf16 v[26:29], v[170:173], v[214:217], v[26:29]
	v_mfma_f32_16x16x32_bf16 v[14:17], v[148:151], v[242:245], v[14:17]
	v_mfma_f32_16x16x32_bf16 v[10:13], v[170:173], v[242:245], v[10:13]
	v_mfma_f32_16x16x32_bf16 v[54:57], v[174:177], v[190:193], v[54:57]
	v_mfma_f32_16x16x32_bf16 v[50:53], v[182:185], v[190:193], v[50:53]
	v_mfma_f32_16x16x32_bf16 v[38:41], v[174:177], v[198:201], v[38:41]
	v_mfma_f32_16x16x32_bf16 v[34:37], v[182:185], v[198:201], v[34:37]
	v_mfma_f32_16x16x32_bf16 v[22:25], v[174:177], v[210:213], v[22:25]
	v_mfma_f32_16x16x32_bf16 v[18:21], v[182:185], v[210:213], v[18:21]
	v_mfma_f32_16x16x32_bf16 v[6:9], v[174:177], v[238:241], v[6:9]
	v_mfma_f32_16x16x32_bf16 v[2:5], v[182:185], v[238:241], v[2:5]
	v_mfma_f32_16x16x32_bf16 v[54:57], v[178:181], v[194:197], v[54:57]
	v_mfma_f32_16x16x32_bf16 v[50:53], v[186:189], v[194:197], v[50:53]
	v_mfma_f32_16x16x32_bf16 v[38:41], v[178:181], v[206:209], v[38:41]
	v_mfma_f32_16x16x32_bf16 v[34:37], v[186:189], v[206:209], v[34:37]
	v_mfma_f32_16x16x32_bf16 v[22:25], v[178:181], v[214:217], v[22:25]
	v_mfma_f32_16x16x32_bf16 v[18:21], v[186:189], v[214:217], v[18:21]
	v_mfma_f32_16x16x32_bf16 v[6:9], v[178:181], v[242:245], v[6:9]
	v_mfma_f32_16x16x32_bf16 v[2:5], v[186:189], v[242:245], v[2:5]
	s_barrier
	s_add_i32 s76, 0, 0x18000
	v_add_u32_e32 v167, s76, v145
	s_add_i32 s77, 0, 0x1c000
	ds_read_b128 v[140:143], v167
	ds_read_b128 v[148:151], v167 offset:1024
	ds_read_b128 v[152:155], v167 offset:2048
	ds_read_b128 v[170:173], v167 offset:3072
	v_add_u32_e32 v167, s77, v145
	ds_read_b128 v[174:177], v167
	ds_read_b128 v[178:181], v167 offset:1024
	ds_read_b128 v[182:185], v167 offset:2048
	ds_read_b128 v[186:189], v167 offset:3072
	s_add_u32 s30, s30, 0x40000
	s_addc_u32 s31, s31, 0
	s_mov_b32 m0, s61
	v_lshl_add_u64 v[246:247], s[30:31], 0, v[130:131]
	ds_read_b128 v[190:193], v147 offset:32768
	ds_read_b128 v[194:197], v147 offset:33792
	ds_read_b128 v[198:201], v147 offset:34816
	ds_read_b128 v[206:209], v147 offset:35840
	ds_read_b128 v[210:213], v147 offset:36864
	ds_read_b128 v[214:217], v147 offset:37888
	ds_read_b128 v[238:241], v147 offset:38912
	ds_read_b128 v[242:245], v147 offset:39936
	global_load_lds_dwordx4 v[246:247], off
	v_lshl_add_u64 v[246:247], s[30:31], 0, v[132:133]
	s_mov_b32 m0, s64
	s_nop 0
	global_load_lds_dwordx4 v[246:247], off
	s_waitcnt vmcnt(8)
	s_waitcnt lgkmcnt(0)
	s_barrier
	s_waitcnt lgkmcnt(0)
	v_mfma_f32_16x16x32_bf16 v[126:129], v[140:143], v[190:193], v[126:129]
	v_mfma_f32_16x16x32_bf16 v[122:125], v[152:155], v[190:193], v[122:125]
	v_mfma_f32_16x16x32_bf16 v[110:113], v[140:143], v[198:201], v[110:113]
	v_mfma_f32_16x16x32_bf16 v[106:109], v[152:155], v[198:201], v[106:109]
	v_mfma_f32_16x16x32_bf16 v[94:97], v[140:143], v[210:213], v[94:97]
	v_mfma_f32_16x16x32_bf16 v[90:93], v[152:155], v[210:213], v[90:93]
	v_mfma_f32_16x16x32_bf16 v[78:81], v[140:143], v[238:241], v[78:81]
	v_mfma_f32_16x16x32_bf16 v[74:77], v[152:155], v[238:241], v[74:77]
	v_mfma_f32_16x16x32_bf16 v[126:129], v[148:151], v[194:197], v[126:129]
	v_mfma_f32_16x16x32_bf16 v[122:125], v[170:173], v[194:197], v[122:125]
	v_mfma_f32_16x16x32_bf16 v[110:113], v[148:151], v[206:209], v[110:113]
	v_mfma_f32_16x16x32_bf16 v[106:109], v[170:173], v[206:209], v[106:109]
	v_mfma_f32_16x16x32_bf16 v[94:97], v[148:151], v[214:217], v[94:97]
	v_mfma_f32_16x16x32_bf16 v[90:93], v[170:173], v[214:217], v[90:93]
	v_mfma_f32_16x16x32_bf16 v[78:81], v[148:151], v[242:245], v[78:81]
	v_mfma_f32_16x16x32_bf16 v[74:77], v[170:173], v[242:245], v[74:77]
	v_mfma_f32_16x16x32_bf16 v[118:121], v[174:177], v[190:193], v[118:121]
	v_mfma_f32_16x16x32_bf16 v[114:117], v[182:185], v[190:193], v[114:117]
	v_mfma_f32_16x16x32_bf16 v[102:105], v[174:177], v[198:201], v[102:105]
	v_mfma_f32_16x16x32_bf16 v[98:101], v[182:185], v[198:201], v[98:101]
	v_mfma_f32_16x16x32_bf16 v[86:89], v[174:177], v[210:213], v[86:89]
	v_mfma_f32_16x16x32_bf16 v[82:85], v[182:185], v[210:213], v[82:85]
	v_mfma_f32_16x16x32_bf16 v[70:73], v[174:177], v[238:241], v[70:73]
	v_mfma_f32_16x16x32_bf16 v[66:69], v[182:185], v[238:241], v[66:69]
	v_mfma_f32_16x16x32_bf16 v[118:121], v[178:181], v[194:197], v[118:121]
	v_mfma_f32_16x16x32_bf16 v[114:117], v[186:189], v[194:197], v[114:117]
	v_mfma_f32_16x16x32_bf16 v[102:105], v[178:181], v[206:209], v[102:105]
	v_mfma_f32_16x16x32_bf16 v[98:101], v[186:189], v[206:209], v[98:101]
	v_mfma_f32_16x16x32_bf16 v[86:89], v[178:181], v[214:217], v[86:89]
	v_mfma_f32_16x16x32_bf16 v[82:85], v[186:189], v[214:217], v[82:85]
	v_mfma_f32_16x16x32_bf16 v[70:73], v[178:181], v[242:245], v[70:73]
	v_mfma_f32_16x16x32_bf16 v[66:69], v[186:189], v[242:245], v[66:69]
	s_barrier
	s_add_i32 s30, s76, s34
	v_lshl_add_u64 v[156:157], v[156:157], 0, s[22:23]
	s_mov_b32 m0, s30
	ds_read_b128 v[190:193], v147 offset:49152
	ds_read_b128 v[194:197], v147 offset:50176
	ds_read_b128 v[198:201], v147 offset:51200
	ds_read_b128 v[206:209], v147 offset:52224
	ds_read_b128 v[210:213], v147 offset:53248
	ds_read_b128 v[214:217], v147 offset:54272
	ds_read_b128 v[238:241], v147 offset:55296
	ds_read_b128 v[242:245], v147 offset:56320
	global_load_lds_dwordx4 v[156:157], off
	s_add_i32 m0, s30, 0x2000
	s_add_u32 s28, s28, 0x40080
	v_lshl_add_u64 v[156:157], v[202:203], 0, s[22:23]
	s_addc_u32 s29, s29, 0
	s_add_i32 s30, s77, s34
	global_load_lds_dwordx4 v[156:157], off
	v_lshl_add_u64 v[156:157], s[28:29], 0, v[0:1]
	s_mov_b32 m0, s30
	s_nop 0
	global_load_lds_dwordx4 v[156:157], off
	v_lshl_add_u64 v[156:157], s[28:29], 0, v[134:135]
	s_add_i32 m0, s30, 0x2000
	s_nop 0
	global_load_lds_dwordx4 v[156:157], off
	v_lshl_add_u64 v[156:157], v[220:221], 0, s[22:23]
	s_mov_b32 m0, s66
	s_nop 0
	global_load_lds_dwordx4 v[156:157], off
	v_lshl_add_u64 v[156:157], v[226:227], 0, s[22:23]
	s_mov_b32 m0, s67
	s_nop 0
	global_load_lds_dwordx4 v[156:157], off
	s_waitcnt vmcnt(8)
	s_waitcnt lgkmcnt(0)
	s_barrier
	s_waitcnt lgkmcnt(0)
	v_mfma_f32_16x16x32_bf16 v[62:65], v[140:143], v[190:193], v[62:65]
	v_mfma_f32_16x16x32_bf16 v[58:61], v[152:155], v[190:193], v[58:61]
	v_mfma_f32_16x16x32_bf16 v[46:49], v[140:143], v[198:201], v[46:49]
	v_mfma_f32_16x16x32_bf16 v[42:45], v[152:155], v[198:201], v[42:45]
	v_mfma_f32_16x16x32_bf16 v[30:33], v[140:143], v[210:213], v[30:33]
	v_mfma_f32_16x16x32_bf16 v[26:29], v[152:155], v[210:213], v[26:29]
	v_mfma_f32_16x16x32_bf16 v[14:17], v[140:143], v[238:241], v[14:17]
	v_mfma_f32_16x16x32_bf16 v[10:13], v[152:155], v[238:241], v[10:13]
	v_mfma_f32_16x16x32_bf16 v[62:65], v[148:151], v[194:197], v[62:65]
	v_mfma_f32_16x16x32_bf16 v[58:61], v[170:173], v[194:197], v[58:61]
	v_mfma_f32_16x16x32_bf16 v[46:49], v[148:151], v[206:209], v[46:49]
	v_mfma_f32_16x16x32_bf16 v[42:45], v[170:173], v[206:209], v[42:45]
	v_mfma_f32_16x16x32_bf16 v[30:33], v[148:151], v[214:217], v[30:33]
	v_mfma_f32_16x16x32_bf16 v[26:29], v[170:173], v[214:217], v[26:29]
	v_mfma_f32_16x16x32_bf16 v[14:17], v[148:151], v[242:245], v[14:17]
	v_mfma_f32_16x16x32_bf16 v[10:13], v[170:173], v[242:245], v[10:13]
	v_mfma_f32_16x16x32_bf16 v[54:57], v[174:177], v[190:193], v[54:57]
	v_mfma_f32_16x16x32_bf16 v[50:53], v[182:185], v[190:193], v[50:53]
	v_mfma_f32_16x16x32_bf16 v[38:41], v[174:177], v[198:201], v[38:41]
	v_mfma_f32_16x16x32_bf16 v[34:37], v[182:185], v[198:201], v[34:37]
	v_mfma_f32_16x16x32_bf16 v[22:25], v[174:177], v[210:213], v[22:25]
	v_mfma_f32_16x16x32_bf16 v[18:21], v[182:185], v[210:213], v[18:21]
	v_mfma_f32_16x16x32_bf16 v[6:9], v[174:177], v[238:241], v[6:9]
	v_mfma_f32_16x16x32_bf16 v[2:5], v[182:185], v[238:241], v[2:5]
	v_mfma_f32_16x16x32_bf16 v[54:57], v[178:181], v[194:197], v[54:57]
	v_mfma_f32_16x16x32_bf16 v[50:53], v[186:189], v[194:197], v[50:53]
	v_mfma_f32_16x16x32_bf16 v[38:41], v[178:181], v[206:209], v[38:41]
	v_mfma_f32_16x16x32_bf16 v[34:37], v[186:189], v[206:209], v[34:37]
	v_mfma_f32_16x16x32_bf16 v[22:25], v[178:181], v[214:217], v[22:25]
	v_mfma_f32_16x16x32_bf16 v[18:21], v[186:189], v[214:217], v[18:21]
	v_mfma_f32_16x16x32_bf16 v[6:9], v[178:181], v[242:245], v[6:9]
	v_mfma_f32_16x16x32_bf16 v[2:5], v[186:189], v[242:245], v[2:5]
	s_barrier
	s_add_i32 s75, s75, 2
	s_add_u32 s73, s73, 0x100
	s_addc_u32 s74, s74, 0
	s_add_u32 s26, s26, 0x100
	s_addc_u32 s27, s27, 0
	s_cmp_gt_u32 s75, 13
	s_cbranch_scc0 .LBB0_993
	s_setprio 0
	s_and_b64 vcc, exec, s[12:13]
	s_cbranch_vccz .LBB0_996
	s_barrier
